# v68 + GEMM K-loops: m0 write moved ahead of the address op, 32 pad nops removed
# baseline (speedup 1.0000x reference)
; #define PG8_STAGE(bufoff, gbase, voff) do { _Pragma("unroll") for (int _i = 0; _i < 2; ++_i) \
;         __builtin_amdgcn_global_load_lds((const unsigned*)((const char*)(gbase) + (voff)[_i]), (PG8_LAS unsigned*)(lds + (bufoff) + ldsw + _i * 8192), 16, 0, 0); } while (0)
; #define PG8_LDA(dst, b, h) do { _Pragma("unroll") for (int m = 0; m < 4; ++m) _Pragma("unroll") for (int k = 0; k < 2; ++k) dst[m][k] = *(const PG8_LAS bf16x8*)(lds + PG8_SA(b, h) + aoff + m * 2048 + k * 1024); } while (0)
; #define PG8_LDB(dst, b, h) do { _Pragma("unroll") for (int n = 0; n < 2; ++n) _Pragma("unroll") for (int k = 0; k < 2; ++k) dst[n][k] = *(const PG8_LAS bf16x8*)(lds + PG8_SB(b, h) + boff + n * 2048 + k * 1024); } while (0)
; #define PG8_MMA(ai, bj, At, Bt) do { __builtin_amdgcn_s_setprio(1); _Pragma("unroll") for (int m = 0; m < 4; ++m) _Pragma("unroll") for (int n = 0; n < 2; ++n) _Pragma("unroll") for (int k = 0; k < 2; ++k) \
;         acc[ai][bj][m][n] = __builtin_amdgcn_mfma_f32_16x16x32_bf16(Bt[n][k], At[m][k], acc[ai][bj][m][n], 0, 0, 0); __builtin_amdgcn_s_setprio(0); } while (0)
; #define PG8_WAIT_V(n) asm volatile("s_waitcnt vmcnt(" #n ")" ::: "memory")
; #define PG8_BAR __builtin_amdgcn_s_barrier()
; template <class Epi, class Sched, bool ALIGN_EPI = false, bool SP2 = false>
; __device__ __forceinline__ void gemm_phase(PG8_LAS unsigned char* lds, const Gemm g, const Sched& S, const Epi& E) {
;     ...
;         for (int t = 0; t < nt; t += 2) {
;             const bool last = (t == nt - 2);
;             const char* a1 = cA + (size_t)(t + 1) * kstep;
;             const char* a2 = last ? nA : cA + (size_t)(t + 2) * kstep; const char* b2 = last ? nB : cB + (size_t)(t + 2) * kstep;
;             const char* a3 = a2 + kstep; const char* b3 = b2 + kstep;
;             if (last && has_next) S.a_ready(nxt);
;             if constexpr (SP2) {
;             PG8_LDB(B0, 0, 0); PG8_LDB(B1, 0, 1); PG8_SCHED; PG8_LDA(At, 0, 0); PG8_STAGE(PG8_SA(1, 1), a1 + hstep, voffA);
;             PG8_WAIT_V(8); PG8_WAIT_L(0); PG8_BAR; PG8_MMA(0, 0, At, B0); PG8_MMA(0, 1, At, B1); PG8_BAR; PG8_SCHED;
;             PG8_LDA(At, 0, 1); PG8_STAGE(PG8_SB(0, 0), b2, voffB); PG8_STAGE(PG8_SB(0, 1), b2 + hstep, voffB); PG8_STAGE(PG8_SA(0, 0), a2, voffA);
;             PG8_WAIT_V(8); PG8_WAIT_L(0); PG8_BAR; PG8_MMA(1, 0, At, B0); PG8_MMA(1, 1, At, B1); PG8_BAR; PG8_SCHED;
.LBB0_100:
	s_add_u32 s28, s8, 0xfffc0080
	s_addc_u32 s29, s9, -1
	s_add_i32 s53, 0, 0x10000
	s_cmp_eq_u32 s45, 12
	s_cselect_b32 s31, s3, s29
	s_cselect_b32 s30, s7, s28
	s_cselect_b32 s29, s11, s44
	s_cselect_b32 s28, s21, s23
	s_add_i32 s56, 0, 0x14000
	v_add_u32_e32 v144, s53, v204
	v_add_u32_e32 v160, s56, v204
	ds_read_b128 v[132:135], v144
	ds_read_b128 v[136:139], v144 offset:1024
	ds_read_b128 v[140:143], v144 offset:2048
	ds_read_b128 v[144:147], v144 offset:3072
	ds_read_b128 v[148:151], v160
	ds_read_b128 v[152:155], v160 offset:1024
	ds_read_b128 v[156:159], v160 offset:2048
	ds_read_b128 v[160:163], v160 offset:3072
	v_lshl_add_u64 v[194:195], s[8:9], 0, v[178:179]
	s_add_i32 m0, s42, 0xc000
	ds_read_b128 v[164:167], v205
	ds_read_b128 v[182:185], v205 offset:1024
	ds_read_b128 v[186:189], v205 offset:2048
	ds_read_b128 v[190:193], v205 offset:3072
	ds_read_b128 v[208:211], v205 offset:4096
	ds_read_b128 v[212:215], v205 offset:5120
	ds_read_b128 v[216:219], v205 offset:6144
	ds_read_b128 v[220:223], v205 offset:7168
	global_load_lds_dwordx4 v[194:195], off
	s_add_i32 m0, s42, 0xe000
	v_lshl_add_u64 v[194:195], s[8:9], 0, v[180:181]
	global_load_lds_dwordx4 v[194:195], off
	s_waitcnt vmcnt(8)
	s_waitcnt lgkmcnt(0)
	s_barrier
	s_setprio 1
	s_waitcnt lgkmcnt(0)
	v_mfma_f32_16x16x32_bf16 v[128:131], v[132:135], v[164:167], v[128:131]
	v_mfma_f32_16x16x32_bf16 v[124:127], v[140:143], v[164:167], v[124:127]
	v_mfma_f32_16x16x32_bf16 v[112:115], v[132:135], v[186:189], v[112:115]
	v_mfma_f32_16x16x32_bf16 v[108:111], v[140:143], v[186:189], v[108:111]
	v_mfma_f32_16x16x32_bf16 v[96:99], v[132:135], v[208:211], v[96:99]
	v_mfma_f32_16x16x32_bf16 v[92:95], v[140:143], v[208:211], v[92:95]
	v_mfma_f32_16x16x32_bf16 v[80:83], v[132:135], v[216:219], v[80:83]
	v_mfma_f32_16x16x32_bf16 v[76:79], v[140:143], v[216:219], v[76:79]
	v_mfma_f32_16x16x32_bf16 v[128:131], v[136:139], v[182:185], v[128:131]
	v_mfma_f32_16x16x32_bf16 v[124:127], v[144:147], v[182:185], v[124:127]
	v_mfma_f32_16x16x32_bf16 v[112:115], v[136:139], v[190:193], v[112:115]
	v_mfma_f32_16x16x32_bf16 v[108:111], v[144:147], v[190:193], v[108:111]
	v_mfma_f32_16x16x32_bf16 v[96:99], v[136:139], v[212:215], v[96:99]
	v_mfma_f32_16x16x32_bf16 v[92:95], v[144:147], v[212:215], v[92:95]
	v_mfma_f32_16x16x32_bf16 v[80:83], v[136:139], v[220:223], v[80:83]
	v_mfma_f32_16x16x32_bf16 v[76:79], v[144:147], v[220:223], v[76:79]
	s_setprio 0
	s_setprio 1
	v_mfma_f32_16x16x32_bf16 v[120:123], v[148:151], v[164:167], v[120:123]
	v_mfma_f32_16x16x32_bf16 v[116:119], v[156:159], v[164:167], v[116:119]
	v_mfma_f32_16x16x32_bf16 v[104:107], v[148:151], v[186:189], v[104:107]
	v_mfma_f32_16x16x32_bf16 v[100:103], v[156:159], v[186:189], v[100:103]
	v_mfma_f32_16x16x32_bf16 v[88:91], v[148:151], v[208:211], v[88:91]
	v_mfma_f32_16x16x32_bf16 v[84:87], v[156:159], v[208:211], v[84:87]
	v_mfma_f32_16x16x32_bf16 v[72:75], v[148:151], v[216:219], v[72:75]
	v_mfma_f32_16x16x32_bf16 v[68:71], v[156:159], v[216:219], v[68:71]
	v_mfma_f32_16x16x32_bf16 v[120:123], v[152:155], v[182:185], v[120:123]
	v_mfma_f32_16x16x32_bf16 v[116:119], v[160:163], v[182:185], v[116:119]
	v_mfma_f32_16x16x32_bf16 v[104:107], v[152:155], v[190:193], v[104:107]
	v_mfma_f32_16x16x32_bf16 v[100:103], v[160:163], v[190:193], v[100:103]
	v_mfma_f32_16x16x32_bf16 v[88:91], v[152:155], v[212:215], v[88:91]
	v_mfma_f32_16x16x32_bf16 v[84:87], v[160:163], v[212:215], v[84:87]
	v_mfma_f32_16x16x32_bf16 v[72:75], v[152:155], v[220:223], v[72:75]
	v_mfma_f32_16x16x32_bf16 v[68:71], v[160:163], v[220:223], v[68:71]
	s_setprio 0
	s_barrier
	s_add_i32 s53, s53, s41
	v_lshl_add_u64 v[194:195], s[28:29], 0, v[168:169]
	s_mov_b32 m0, s53
	ds_read_b128 v[164:167], v205 offset:16384
	ds_read_b128 v[182:185], v205 offset:17408
	ds_read_b128 v[186:189], v205 offset:18432
	ds_read_b128 v[190:193], v205 offset:19456
	ds_read_b128 v[208:211], v205 offset:20480
	ds_read_b128 v[212:215], v205 offset:21504
	ds_read_b128 v[216:219], v205 offset:22528
	ds_read_b128 v[220:223], v205 offset:23552
	global_load_lds_dwordx4 v[194:195], off
	s_add_i32 m0, s53, 0x2000
	s_add_u32 s54, s28, 0x40000
	v_lshl_add_u64 v[202:203], s[28:29], 0, v[172:173]
	s_addc_u32 s55, s29, 0
	s_add_i32 s53, s56, s41
	global_load_lds_dwordx4 v[202:203], off
	v_lshl_add_u64 v[224:225], s[54:55], 0, v[168:169]
	s_mov_b32 m0, s53
	v_lshl_add_u64 v[226:227], s[30:31], 0, v[170:171]
	global_load_lds_dwordx4 v[224:225], off
	s_add_i32 m0, s53, 0x2000
	v_lshl_add_u64 v[224:225], s[54:55], 0, v[172:173]
	global_load_lds_dwordx4 v[224:225], off
	s_mov_b32 m0, s42
	v_lshl_add_u64 v[224:225], s[30:31], 0, v[0:1]
	global_load_lds_dwordx4 v[224:225], off
	s_mov_b32 m0, s43
	s_nop 0
	global_load_lds_dwordx4 v[226:227], off
	s_waitcnt vmcnt(8)
	s_waitcnt lgkmcnt(0)
	s_barrier
; #define PG8_STAGE(bufoff, gbase, voff) do { _Pragma("unroll") for (int _i = 0; _i < 2; ++_i) \
;         __builtin_amdgcn_global_load_lds((const unsigned*)((const char*)(gbase) + (voff)[_i]), (PG8_LAS unsigned*)(lds + (bufoff) + ldsw + _i * 8192), 16, 0, 0); } while (0)
; #define PG8_LDA(dst, b, h) do { _Pragma("unroll") for (int m = 0; m < 4; ++m) _Pragma("unroll") for (int k = 0; k < 2; ++k) dst[m][k] = *(const PG8_LAS bf16x8*)(lds + PG8_SA(b, h) + aoff + m * 2048 + k * 1024); } while (0)
; #define PG8_LDB(dst, b, h) do { _Pragma("unroll") for (int n = 0; n < 2; ++n) _Pragma("unroll") for (int k = 0; k < 2; ++k) dst[n][k] = *(const PG8_LAS bf16x8*)(lds + PG8_SB(b, h) + boff + n * 2048 + k * 1024); } while (0)
; #define PG8_MMA(ai, bj, At, Bt) do { __builtin_amdgcn_s_setprio(1); _Pragma("unroll") for (int m = 0; m < 4; ++m) _Pragma("unroll") for (int n = 0; n < 2; ++n) _Pragma("unroll") for (int k = 0; k < 2; ++k) \
;         acc[ai][bj][m][n] = __builtin_amdgcn_mfma_f32_16x16x32_bf16(Bt[n][k], At[m][k], acc[ai][bj][m][n], 0, 0, 0); __builtin_amdgcn_s_setprio(0); } while (0)
; #define PG8_WAIT_V(n) asm volatile("s_waitcnt vmcnt(" #n ")" ::: "memory")
; #define PG8_WAIT_L(n) asm volatile("s_waitcnt lgkmcnt(" #n ")" ::: "memory")
; #define PG8_BAR __builtin_amdgcn_s_barrier()
; #define PG8_SCHED __builtin_amdgcn_sched_barrier(0)
; template <class Epi, class Sched, bool ALIGN_EPI = false, bool SP2 = false>
; __device__ __forceinline__ void gemm_phase(PG8_LAS unsigned char* lds, const Gemm g, const Sched& S, const Epi& E) {
;     ...
;             PG8_WAIT_V(8); PG8_WAIT_L(0); PG8_BAR; PG8_MMA(1, 0, At, B0); PG8_MMA(1, 1, At, B1); PG8_BAR; PG8_SCHED;
;             PG8_LDB(B0, 1, 0); PG8_LDB(B1, 1, 1); PG8_SCHED; PG8_LDA(At, 1, 0); PG8_STAGE(PG8_SA(0, 1), a2 + hstep, voffA);
;             PG8_WAIT_V(8); PG8_WAIT_L(0); PG8_BAR; PG8_MMA(0, 0, At, B0); PG8_MMA(0, 1, At, B1); PG8_BAR; PG8_SCHED;
	s_setprio 1
	s_waitcnt lgkmcnt(0)
	v_mfma_f32_16x16x32_bf16 v[64:67], v[132:135], v[164:167], v[64:67]
	v_mfma_f32_16x16x32_bf16 v[60:63], v[140:143], v[164:167], v[60:63]
	v_mfma_f32_16x16x32_bf16 v[48:51], v[132:135], v[186:189], v[48:51]
	v_mfma_f32_16x16x32_bf16 v[44:47], v[140:143], v[186:189], v[44:47]
	v_mfma_f32_16x16x32_bf16 v[32:35], v[132:135], v[208:211], v[32:35]
	v_mfma_f32_16x16x32_bf16 v[28:31], v[140:143], v[208:211], v[28:31]
	v_mfma_f32_16x16x32_bf16 v[16:19], v[132:135], v[216:219], v[16:19]
	v_mfma_f32_16x16x32_bf16 v[12:15], v[140:143], v[216:219], v[12:15]
	v_mfma_f32_16x16x32_bf16 v[64:67], v[136:139], v[182:185], v[64:67]
	v_mfma_f32_16x16x32_bf16 v[60:63], v[144:147], v[182:185], v[60:63]
	v_mfma_f32_16x16x32_bf16 v[48:51], v[136:139], v[190:193], v[48:51]
	v_mfma_f32_16x16x32_bf16 v[44:47], v[144:147], v[190:193], v[44:47]
	v_mfma_f32_16x16x32_bf16 v[32:35], v[136:139], v[212:215], v[32:35]
	v_mfma_f32_16x16x32_bf16 v[28:31], v[144:147], v[212:215], v[28:31]
	v_mfma_f32_16x16x32_bf16 v[16:19], v[136:139], v[220:223], v[16:19]
	v_mfma_f32_16x16x32_bf16 v[12:15], v[144:147], v[220:223], v[12:15]
	s_setprio 0
	s_setprio 1
	v_mfma_f32_16x16x32_bf16 v[56:59], v[148:151], v[164:167], v[56:59]
	v_mfma_f32_16x16x32_bf16 v[52:55], v[156:159], v[164:167], v[52:55]
	v_mfma_f32_16x16x32_bf16 v[40:43], v[148:151], v[186:189], v[40:43]
	v_mfma_f32_16x16x32_bf16 v[36:39], v[156:159], v[186:189], v[36:39]
	v_mfma_f32_16x16x32_bf16 v[24:27], v[148:151], v[208:211], v[24:27]
	v_mfma_f32_16x16x32_bf16 v[20:23], v[156:159], v[208:211], v[20:23]
	v_mfma_f32_16x16x32_bf16 v[8:11], v[148:151], v[216:219], v[8:11]
	v_mfma_f32_16x16x32_bf16 v[4:7], v[156:159], v[216:219], v[4:7]
	v_mfma_f32_16x16x32_bf16 v[56:59], v[152:155], v[182:185], v[56:59]
	v_mfma_f32_16x16x32_bf16 v[52:55], v[160:163], v[182:185], v[52:55]
	v_mfma_f32_16x16x32_bf16 v[40:43], v[152:155], v[190:193], v[40:43]
	v_mfma_f32_16x16x32_bf16 v[36:39], v[160:163], v[190:193], v[36:39]
	v_mfma_f32_16x16x32_bf16 v[24:27], v[152:155], v[212:215], v[24:27]
	v_mfma_f32_16x16x32_bf16 v[20:23], v[160:163], v[212:215], v[20:23]
	v_mfma_f32_16x16x32_bf16 v[8:11], v[152:155], v[220:223], v[8:11]
	v_mfma_f32_16x16x32_bf16 v[4:7], v[160:163], v[220:223], v[4:7]
	s_setprio 0
	s_barrier
	s_add_i32 s53, 0, 0x18000
	s_add_i32 s54, 0, 0x1c000
	v_add_u32_e32 v144, s53, v204
	v_add_u32_e32 v160, s54, v204
	ds_read_b128 v[132:135], v144
	ds_read_b128 v[136:139], v144 offset:1024
	ds_read_b128 v[140:143], v144 offset:2048
	ds_read_b128 v[144:147], v144 offset:3072
	ds_read_b128 v[148:151], v160
	ds_read_b128 v[152:155], v160 offset:1024
	ds_read_b128 v[156:159], v160 offset:2048
	ds_read_b128 v[160:163], v160 offset:3072
	s_add_u32 s30, s30, 0x40000
	s_addc_u32 s31, s31, 0
	s_mov_b32 m0, s46
	v_lshl_add_u64 v[228:229], s[30:31], 0, v[0:1]
	ds_read_b128 v[164:167], v205 offset:32768
	ds_read_b128 v[182:185], v205 offset:33792
	ds_read_b128 v[186:189], v205 offset:34816
	ds_read_b128 v[190:193], v205 offset:35840
	ds_read_b128 v[208:211], v205 offset:36864
	ds_read_b128 v[212:215], v205 offset:37888
	ds_read_b128 v[216:219], v205 offset:38912
	ds_read_b128 v[220:223], v205 offset:39936
	global_load_lds_dwordx4 v[228:229], off
	s_mov_b32 m0, s47
	v_lshl_add_u64 v[228:229], s[30:31], 0, v[170:171]
	global_load_lds_dwordx4 v[228:229], off
	s_waitcnt vmcnt(8)
	s_waitcnt lgkmcnt(0)
	s_barrier
	s_setprio 1
	s_waitcnt lgkmcnt(0)
	v_mfma_f32_16x16x32_bf16 v[128:131], v[132:135], v[164:167], v[128:131]
	v_mfma_f32_16x16x32_bf16 v[124:127], v[140:143], v[164:167], v[124:127]
	v_mfma_f32_16x16x32_bf16 v[112:115], v[132:135], v[186:189], v[112:115]
	v_mfma_f32_16x16x32_bf16 v[108:111], v[140:143], v[186:189], v[108:111]
	v_mfma_f32_16x16x32_bf16 v[96:99], v[132:135], v[208:211], v[96:99]
	v_mfma_f32_16x16x32_bf16 v[92:95], v[140:143], v[208:211], v[92:95]
	v_mfma_f32_16x16x32_bf16 v[80:83], v[132:135], v[216:219], v[80:83]
	v_mfma_f32_16x16x32_bf16 v[76:79], v[140:143], v[216:219], v[76:79]
	v_mfma_f32_16x16x32_bf16 v[128:131], v[136:139], v[182:185], v[128:131]
	v_mfma_f32_16x16x32_bf16 v[124:127], v[144:147], v[182:185], v[124:127]
	v_mfma_f32_16x16x32_bf16 v[112:115], v[136:139], v[190:193], v[112:115]
	v_mfma_f32_16x16x32_bf16 v[108:111], v[144:147], v[190:193], v[108:111]
	v_mfma_f32_16x16x32_bf16 v[96:99], v[136:139], v[212:215], v[96:99]
	v_mfma_f32_16x16x32_bf16 v[92:95], v[144:147], v[212:215], v[92:95]
	v_mfma_f32_16x16x32_bf16 v[80:83], v[136:139], v[220:223], v[80:83]
	v_mfma_f32_16x16x32_bf16 v[76:79], v[144:147], v[220:223], v[76:79]
	s_setprio 0
	s_setprio 1
	v_mfma_f32_16x16x32_bf16 v[120:123], v[148:151], v[164:167], v[120:123]
	v_mfma_f32_16x16x32_bf16 v[116:119], v[156:159], v[164:167], v[116:119]
	v_mfma_f32_16x16x32_bf16 v[104:107], v[148:151], v[186:189], v[104:107]
	v_mfma_f32_16x16x32_bf16 v[100:103], v[156:159], v[186:189], v[100:103]
	v_mfma_f32_16x16x32_bf16 v[88:91], v[148:151], v[208:211], v[88:91]
	v_mfma_f32_16x16x32_bf16 v[84:87], v[156:159], v[208:211], v[84:87]
	v_mfma_f32_16x16x32_bf16 v[72:75], v[148:151], v[216:219], v[72:75]
	v_mfma_f32_16x16x32_bf16 v[68:71], v[156:159], v[216:219], v[68:71]
	v_mfma_f32_16x16x32_bf16 v[120:123], v[152:155], v[182:185], v[120:123]
	v_mfma_f32_16x16x32_bf16 v[116:119], v[160:163], v[182:185], v[116:119]
	v_mfma_f32_16x16x32_bf16 v[104:107], v[152:155], v[190:193], v[104:107]
	v_mfma_f32_16x16x32_bf16 v[100:103], v[160:163], v[190:193], v[100:103]
	v_mfma_f32_16x16x32_bf16 v[88:91], v[152:155], v[212:215], v[88:91]
	v_mfma_f32_16x16x32_bf16 v[84:87], v[160:163], v[212:215], v[84:87]
	v_mfma_f32_16x16x32_bf16 v[72:75], v[152:155], v[220:223], v[72:75]
	v_mfma_f32_16x16x32_bf16 v[68:71], v[160:163], v[220:223], v[68:71]
	s_setprio 0
	s_barrier
; #define PG8_STAGE(bufoff, gbase, voff) do { _Pragma("unroll") for (int _i = 0; _i < 2; ++_i) \
;         __builtin_amdgcn_global_load_lds((const unsigned*)((const char*)(gbase) + (voff)[_i]), (PG8_LAS unsigned*)(lds + (bufoff) + ldsw + _i * 8192), 16, 0, 0); } while (0)
; #define PG8_LDA(dst, b, h) do { _Pragma("unroll") for (int m = 0; m < 4; ++m) _Pragma("unroll") for (int k = 0; k < 2; ++k) dst[m][k] = *(const PG8_LAS bf16x8*)(lds + PG8_SA(b, h) + aoff + m * 2048 + k * 1024); } while (0)
; #define PG8_MMA(ai, bj, At, Bt) do { __builtin_amdgcn_s_setprio(1); _Pragma("unroll") for (int m = 0; m < 4; ++m) _Pragma("unroll") for (int n = 0; n < 2; ++n) _Pragma("unroll") for (int k = 0; k < 2; ++k) \
;         acc[ai][bj][m][n] = __builtin_amdgcn_mfma_f32_16x16x32_bf16(Bt[n][k], At[m][k], acc[ai][bj][m][n], 0, 0, 0); __builtin_amdgcn_s_setprio(0); } while (0)
; #define PG8_WAIT_V(n) asm volatile("s_waitcnt vmcnt(" #n ")" ::: "memory")
; #define PG8_WAIT_L(n) asm volatile("s_waitcnt lgkmcnt(" #n ")" ::: "memory")
; #define PG8_BAR __builtin_amdgcn_s_barrier()
; #define PG8_SCHED __builtin_amdgcn_sched_barrier(0)
; template <class Epi, class Sched, bool ALIGN_EPI = false, bool SP2 = false>
; __device__ __forceinline__ void gemm_phase(PG8_LAS unsigned char* lds, const Gemm g, const Sched& S, const Epi& E) {
;     ...
;             PG8_LDA(At, 1, 1); PG8_STAGE(PG8_SB(1, 0), b3, voffB); PG8_STAGE(PG8_SB(1, 1), b3 + hstep, voffB); PG8_STAGE(PG8_SA(1, 0), a3, voffA);
;             PG8_WAIT_V(8); PG8_WAIT_L(0); PG8_BAR; PG8_MMA(1, 0, At, B0); PG8_MMA(1, 1, At, B1); PG8_BAR; PG8_SCHED;
;     ...
;         if constexpr (ALIGN_EPI) { if (wr == 0) PG8_BAR; }
	s_add_i32 s30, s53, s41
	v_lshl_add_u64 v[194:195], v[194:195], 0, s[82:83]
	s_mov_b32 m0, s30
	ds_read_b128 v[164:167], v205 offset:49152
	ds_read_b128 v[182:185], v205 offset:50176
	ds_read_b128 v[186:189], v205 offset:51200
	ds_read_b128 v[190:193], v205 offset:52224
	ds_read_b128 v[208:211], v205 offset:53248
	ds_read_b128 v[212:215], v205 offset:54272
	ds_read_b128 v[216:219], v205 offset:55296
	ds_read_b128 v[220:223], v205 offset:56320
	global_load_lds_dwordx4 v[194:195], off
	s_add_i32 m0, s30, 0x2000
	s_add_u32 s28, s28, 0x40080
	v_lshl_add_u64 v[194:195], v[202:203], 0, s[82:83]
	s_addc_u32 s29, s29, 0
	s_add_i32 s30, s54, s41
	global_load_lds_dwordx4 v[194:195], off
	s_mov_b32 m0, s30
	v_lshl_add_u64 v[194:195], s[28:29], 0, v[168:169]
	global_load_lds_dwordx4 v[194:195], off
	s_add_i32 m0, s30, 0x2000
	v_lshl_add_u64 v[194:195], s[28:29], 0, v[172:173]
	global_load_lds_dwordx4 v[194:195], off
	s_mov_b32 m0, s50
	v_lshl_add_u64 v[194:195], v[224:225], 0, s[82:83]
	global_load_lds_dwordx4 v[194:195], off
	s_mov_b32 m0, s51
	v_lshl_add_u64 v[194:195], v[226:227], 0, s[82:83]
	global_load_lds_dwordx4 v[194:195], off
	s_waitcnt vmcnt(8)
	s_waitcnt lgkmcnt(0)
	s_barrier
	s_setprio 1
	s_waitcnt lgkmcnt(0)
	v_mfma_f32_16x16x32_bf16 v[64:67], v[132:135], v[164:167], v[64:67]
	v_mfma_f32_16x16x32_bf16 v[60:63], v[140:143], v[164:167], v[60:63]
	v_mfma_f32_16x16x32_bf16 v[48:51], v[132:135], v[186:189], v[48:51]
	v_mfma_f32_16x16x32_bf16 v[44:47], v[140:143], v[186:189], v[44:47]
	v_mfma_f32_16x16x32_bf16 v[32:35], v[132:135], v[208:211], v[32:35]
	v_mfma_f32_16x16x32_bf16 v[28:31], v[140:143], v[208:211], v[28:31]
	v_mfma_f32_16x16x32_bf16 v[16:19], v[132:135], v[216:219], v[16:19]
	v_mfma_f32_16x16x32_bf16 v[12:15], v[140:143], v[216:219], v[12:15]
	v_mfma_f32_16x16x32_bf16 v[64:67], v[136:139], v[182:185], v[64:67]
	v_mfma_f32_16x16x32_bf16 v[60:63], v[144:147], v[182:185], v[60:63]
	v_mfma_f32_16x16x32_bf16 v[48:51], v[136:139], v[190:193], v[48:51]
	v_mfma_f32_16x16x32_bf16 v[44:47], v[144:147], v[190:193], v[44:47]
	v_mfma_f32_16x16x32_bf16 v[32:35], v[136:139], v[212:215], v[32:35]
	v_mfma_f32_16x16x32_bf16 v[28:31], v[144:147], v[212:215], v[28:31]
	v_mfma_f32_16x16x32_bf16 v[16:19], v[136:139], v[220:223], v[16:19]
	v_mfma_f32_16x16x32_bf16 v[12:15], v[144:147], v[220:223], v[12:15]
	s_setprio 0
	s_setprio 1
	v_mfma_f32_16x16x32_bf16 v[56:59], v[148:151], v[164:167], v[56:59]
	v_mfma_f32_16x16x32_bf16 v[52:55], v[156:159], v[164:167], v[52:55]
	v_mfma_f32_16x16x32_bf16 v[40:43], v[148:151], v[186:189], v[40:43]
	v_mfma_f32_16x16x32_bf16 v[36:39], v[156:159], v[186:189], v[36:39]
	v_mfma_f32_16x16x32_bf16 v[24:27], v[148:151], v[208:211], v[24:27]
	v_mfma_f32_16x16x32_bf16 v[20:23], v[156:159], v[208:211], v[20:23]
	v_mfma_f32_16x16x32_bf16 v[8:11], v[148:151], v[216:219], v[8:11]
	v_mfma_f32_16x16x32_bf16 v[4:7], v[156:159], v[216:219], v[4:7]
	v_mfma_f32_16x16x32_bf16 v[56:59], v[152:155], v[182:185], v[56:59]
	v_mfma_f32_16x16x32_bf16 v[52:55], v[160:163], v[182:185], v[52:55]
	v_mfma_f32_16x16x32_bf16 v[40:43], v[152:155], v[190:193], v[40:43]
	v_mfma_f32_16x16x32_bf16 v[36:39], v[160:163], v[190:193], v[36:39]
	v_mfma_f32_16x16x32_bf16 v[24:27], v[152:155], v[212:215], v[24:27]
	v_mfma_f32_16x16x32_bf16 v[20:23], v[160:163], v[212:215], v[20:23]
	v_mfma_f32_16x16x32_bf16 v[8:11], v[152:155], v[220:223], v[8:11]
	v_mfma_f32_16x16x32_bf16 v[4:7], v[160:163], v[220:223], v[4:7]
	s_setprio 0
	s_barrier
	s_add_i32 s45, s45, 2
	s_add_u32 s8, s8, 0x100
	s_addc_u32 s9, s9, 0
	s_add_u32 s23, s23, 0x100
	s_addc_u32 s44, s44, 0
	s_cmp_gt_u32 s45, 13
	s_cbranch_scc0 .LBB0_100
	s_and_b64 vcc, exec, s[14:15]
	s_cbranch_vccz .LBB0_103
	s_barrier

; #define PG8_STAGE(bufoff, gbase, voff) do { _Pragma("unroll") for (int _i = 0; _i < 2; ++_i) \
;         __builtin_amdgcn_global_load_lds((const unsigned*)((const char*)(gbase) + (voff)[_i]), (PG8_LAS unsigned*)(lds + (bufoff) + ldsw + _i * 8192), 16, 0, 0); } while (0)
; #define PG8_LDA(dst, b, h) do { _Pragma("unroll") for (int m = 0; m < 4; ++m) _Pragma("unroll") for (int k = 0; k < 2; ++k) dst[m][k] = *(const PG8_LAS bf16x8*)(lds + PG8_SA(b, h) + aoff + m * 2048 + k * 1024); } while (0)
; #define PG8_LDB(dst, b, h) do { _Pragma("unroll") for (int n = 0; n < 2; ++n) _Pragma("unroll") for (int k = 0; k < 2; ++k) dst[n][k] = *(const PG8_LAS bf16x8*)(lds + PG8_SB(b, h) + boff + n * 2048 + k * 1024); } while (0)
; #define PG8_MMA(ai, bj, At, Bt) do { __builtin_amdgcn_s_setprio(1); _Pragma("unroll") for (int m = 0; m < 4; ++m) _Pragma("unroll") for (int n = 0; n < 2; ++n) _Pragma("unroll") for (int k = 0; k < 2; ++k) \
;         acc[ai][bj][m][n] = __builtin_amdgcn_mfma_f32_16x16x32_bf16(Bt[n][k], At[m][k], acc[ai][bj][m][n], 0, 0, 0); __builtin_amdgcn_s_setprio(0); } while (0)
; #define PG8_WAIT_V(n) asm volatile("s_waitcnt vmcnt(" #n ")" ::: "memory")
; #define PG8_BAR __builtin_amdgcn_s_barrier()
; template <class Epi, class Sched, bool ALIGN_EPI = false, bool SP2 = false>
; __device__ __forceinline__ void gemm_phase(PG8_LAS unsigned char* lds, const Gemm g, const Sched& S, const Epi& E) {
;     ...
;         for (int t = 0; t < nt; t += 2) {
;             const bool last = (t == nt - 2);
;             const char* a1 = cA + (size_t)(t + 1) * kstep;
;             const char* a2 = last ? nA : cA + (size_t)(t + 2) * kstep; const char* b2 = last ? nB : cB + (size_t)(t + 2) * kstep;
;             const char* a3 = a2 + kstep; const char* b3 = b2 + kstep;
;             if (last && has_next) S.a_ready(nxt);
;             if constexpr (SP2) {
;             PG8_LDB(B0, 0, 0); PG8_LDB(B1, 0, 1); PG8_SCHED; PG8_LDA(At, 0, 0); PG8_STAGE(PG8_SA(1, 1), a1 + hstep, voffA);
;             PG8_WAIT_V(8); PG8_WAIT_L(0); PG8_BAR; PG8_MMA(0, 0, At, B0); PG8_MMA(0, 1, At, B1); PG8_BAR; PG8_SCHED;
;             PG8_LDA(At, 0, 1); PG8_STAGE(PG8_SB(0, 0), b2, voffB); PG8_STAGE(PG8_SB(0, 1), b2 + hstep, voffB); PG8_STAGE(PG8_SA(0, 0), a2, voffA);
;             PG8_WAIT_V(8); PG8_WAIT_L(0); PG8_BAR; PG8_MMA(1, 0, At, B0); PG8_MMA(1, 1, At, B1); PG8_BAR; PG8_SCHED;
.LBB0_329:
	s_add_u32 s30, s28, 0xfffc0080
	s_addc_u32 s31, s29, -1
	s_add_i32 s52, 0, 0x10000
	s_cmp_eq_u32 s45, 12
	s_cselect_b32 s35, s3, s31
	s_cselect_b32 s34, s17, s30
	s_cselect_b32 s31, s19, s44
	s_cselect_b32 s30, s25, s27
	s_add_i32 s54, 0, 0x14000
	v_add_u32_e32 v128, s52, v251
	v_add_u32_e32 v156, s54, v251
	ds_read_b128 v[108:111], v128
	ds_read_b128 v[112:115], v128 offset:1024
	ds_read_b128 v[124:127], v128 offset:2048
	ds_read_b128 v[128:131], v128 offset:3072
	ds_read_b128 v[132:135], v156
	ds_read_b128 v[140:143], v156 offset:1024
	ds_read_b128 v[148:151], v156 offset:2048
	ds_read_b128 v[156:159], v156 offset:3072
	v_lshl_add_u64 v[212:213], s[28:29], 0, v[208:209]
	s_add_i32 m0, s42, 0xc000
	ds_read_b128 v[164:167], v253
	ds_read_b128 v[168:171], v253 offset:1024
	ds_read_b128 v[172:175], v253 offset:2048
	ds_read_b128 v[176:179], v253 offset:3072
	ds_read_b128 v[180:183], v253 offset:4096
	ds_read_b128 v[184:187], v253 offset:5120
	ds_read_b128 v[188:191], v253 offset:6144
	ds_read_b128 v[192:195], v253 offset:7168
	global_load_lds_dwordx4 v[212:213], off
	s_add_i32 m0, s42, 0xe000
	v_lshl_add_u64 v[212:213], s[28:29], 0, v[210:211]
	global_load_lds_dwordx4 v[212:213], off
	s_waitcnt vmcnt(8)
	s_waitcnt lgkmcnt(0)
	s_barrier
	s_setprio 1
	s_waitcnt lgkmcnt(0)
	v_mfma_f32_16x16x32_bf16 v[160:163], v[108:111], v[164:167], v[160:163]
	v_mfma_f32_16x16x32_bf16 v[152:155], v[124:127], v[164:167], v[152:155]
	v_mfma_f32_16x16x32_bf16 v[120:123], v[108:111], v[172:175], v[120:123]
	v_mfma_f32_16x16x32_bf16 v[116:119], v[124:127], v[172:175], v[116:119]
	v_mfma_f32_16x16x32_bf16 v[96:99], v[108:111], v[180:183], v[96:99]
	v_mfma_f32_16x16x32_bf16 v[92:95], v[124:127], v[180:183], v[92:95]
	v_mfma_f32_16x16x32_bf16 v[80:83], v[108:111], v[188:191], v[80:83]
	v_mfma_f32_16x16x32_bf16 v[76:79], v[124:127], v[188:191], v[76:79]
	v_mfma_f32_16x16x32_bf16 v[160:163], v[112:115], v[168:171], v[160:163]
	v_mfma_f32_16x16x32_bf16 v[152:155], v[128:131], v[168:171], v[152:155]
	v_mfma_f32_16x16x32_bf16 v[120:123], v[112:115], v[176:179], v[120:123]
	v_mfma_f32_16x16x32_bf16 v[116:119], v[128:131], v[176:179], v[116:119]
	v_mfma_f32_16x16x32_bf16 v[96:99], v[112:115], v[184:187], v[96:99]
	v_mfma_f32_16x16x32_bf16 v[92:95], v[128:131], v[184:187], v[92:95]
	v_mfma_f32_16x16x32_bf16 v[80:83], v[112:115], v[192:195], v[80:83]
	v_mfma_f32_16x16x32_bf16 v[76:79], v[128:131], v[192:195], v[76:79]
	s_setprio 0
	s_setprio 1
	v_mfma_f32_16x16x32_bf16 v[144:147], v[132:135], v[164:167], v[144:147]
	v_mfma_f32_16x16x32_bf16 v[136:139], v[148:151], v[164:167], v[136:139]
	v_mfma_f32_16x16x32_bf16 v[104:107], v[132:135], v[172:175], v[104:107]
	v_mfma_f32_16x16x32_bf16 v[100:103], v[148:151], v[172:175], v[100:103]
	v_mfma_f32_16x16x32_bf16 v[88:91], v[132:135], v[180:183], v[88:91]
	v_mfma_f32_16x16x32_bf16 v[84:87], v[148:151], v[180:183], v[84:87]
	v_mfma_f32_16x16x32_bf16 v[72:75], v[132:135], v[188:191], v[72:75]
	v_mfma_f32_16x16x32_bf16 v[68:71], v[148:151], v[188:191], v[68:71]
	v_mfma_f32_16x16x32_bf16 v[144:147], v[140:143], v[168:171], v[144:147]
	v_mfma_f32_16x16x32_bf16 v[136:139], v[156:159], v[168:171], v[136:139]
	v_mfma_f32_16x16x32_bf16 v[104:107], v[140:143], v[176:179], v[104:107]
	v_mfma_f32_16x16x32_bf16 v[100:103], v[156:159], v[176:179], v[100:103]
	v_mfma_f32_16x16x32_bf16 v[88:91], v[140:143], v[184:187], v[88:91]
	v_mfma_f32_16x16x32_bf16 v[84:87], v[156:159], v[184:187], v[84:87]
	v_mfma_f32_16x16x32_bf16 v[72:75], v[140:143], v[192:195], v[72:75]
	v_mfma_f32_16x16x32_bf16 v[68:71], v[156:159], v[192:195], v[68:71]
	s_setprio 0
	s_barrier
	s_add_i32 s52, s52, s41
	v_lshl_add_u64 v[212:213], s[30:31], 0, v[202:203]
	s_mov_b32 m0, s52
	ds_read_b128 v[164:167], v253 offset:16384
	ds_read_b128 v[168:171], v253 offset:17408
	ds_read_b128 v[172:175], v253 offset:18432
	ds_read_b128 v[176:179], v253 offset:19456
	ds_read_b128 v[180:183], v253 offset:20480
	ds_read_b128 v[184:187], v253 offset:21504
	ds_read_b128 v[188:191], v253 offset:22528
	ds_read_b128 v[192:195], v253 offset:23552
	global_load_lds_dwordx4 v[212:213], off
	s_add_i32 m0, s52, 0x2000
	s_add_u32 s52, s30, 0x40000
	v_lshl_add_u64 v[214:215], s[30:31], 0, v[206:207]
	s_addc_u32 s53, s31, 0
	s_add_i32 s54, s54, s41
	global_load_lds_dwordx4 v[214:215], off
	v_lshl_add_u64 v[216:217], s[52:53], 0, v[202:203]
	s_mov_b32 m0, s54
	v_lshl_add_u64 v[218:219], s[34:35], 0, v[204:205]
	global_load_lds_dwordx4 v[216:217], off
	s_add_i32 m0, s54, 0x2000
	v_lshl_add_u64 v[216:217], s[52:53], 0, v[206:207]
	global_load_lds_dwordx4 v[216:217], off
	s_mov_b32 m0, s42
	v_lshl_add_u64 v[216:217], s[34:35], 0, v[0:1]
	global_load_lds_dwordx4 v[216:217], off
	s_mov_b32 m0, s43
	s_nop 0
	global_load_lds_dwordx4 v[218:219], off
	s_waitcnt vmcnt(8)
	s_waitcnt lgkmcnt(0)
	s_barrier
; #define PG8_STAGE(bufoff, gbase, voff) do { _Pragma("unroll") for (int _i = 0; _i < 2; ++_i) \
;         __builtin_amdgcn_global_load_lds((const unsigned*)((const char*)(gbase) + (voff)[_i]), (PG8_LAS unsigned*)(lds + (bufoff) + ldsw + _i * 8192), 16, 0, 0); } while (0)
; #define PG8_LDA(dst, b, h) do { _Pragma("unroll") for (int m = 0; m < 4; ++m) _Pragma("unroll") for (int k = 0; k < 2; ++k) dst[m][k] = *(const PG8_LAS bf16x8*)(lds + PG8_SA(b, h) + aoff + m * 2048 + k * 1024); } while (0)
; #define PG8_LDB(dst, b, h) do { _Pragma("unroll") for (int n = 0; n < 2; ++n) _Pragma("unroll") for (int k = 0; k < 2; ++k) dst[n][k] = *(const PG8_LAS bf16x8*)(lds + PG8_SB(b, h) + boff + n * 2048 + k * 1024); } while (0)
; #define PG8_MMA(ai, bj, At, Bt) do { __builtin_amdgcn_s_setprio(1); _Pragma("unroll") for (int m = 0; m < 4; ++m) _Pragma("unroll") for (int n = 0; n < 2; ++n) _Pragma("unroll") for (int k = 0; k < 2; ++k) \
;         acc[ai][bj][m][n] = __builtin_amdgcn_mfma_f32_16x16x32_bf16(Bt[n][k], At[m][k], acc[ai][bj][m][n], 0, 0, 0); __builtin_amdgcn_s_setprio(0); } while (0)
; #define PG8_WAIT_V(n) asm volatile("s_waitcnt vmcnt(" #n ")" ::: "memory")
; #define PG8_WAIT_L(n) asm volatile("s_waitcnt lgkmcnt(" #n ")" ::: "memory")
; #define PG8_BAR __builtin_amdgcn_s_barrier()
; #define PG8_SCHED __builtin_amdgcn_sched_barrier(0)
; template <class Epi, class Sched, bool ALIGN_EPI = false, bool SP2 = false>
; __device__ __forceinline__ void gemm_phase(PG8_LAS unsigned char* lds, const Gemm g, const Sched& S, const Epi& E) {
;     ...
;             PG8_WAIT_V(8); PG8_WAIT_L(0); PG8_BAR; PG8_MMA(1, 0, At, B0); PG8_MMA(1, 1, At, B1); PG8_BAR; PG8_SCHED;
;             PG8_LDB(B0, 1, 0); PG8_LDB(B1, 1, 1); PG8_SCHED; PG8_LDA(At, 1, 0); PG8_STAGE(PG8_SA(0, 1), a2 + hstep, voffA);
;             PG8_WAIT_V(8); PG8_WAIT_L(0); PG8_BAR; PG8_MMA(0, 0, At, B0); PG8_MMA(0, 1, At, B1); PG8_BAR; PG8_SCHED;
	s_setprio 1
	s_waitcnt lgkmcnt(0)
	v_mfma_f32_16x16x32_bf16 v[64:67], v[108:111], v[164:167], v[64:67]
	v_mfma_f32_16x16x32_bf16 v[60:63], v[124:127], v[164:167], v[60:63]
	v_mfma_f32_16x16x32_bf16 v[48:51], v[108:111], v[172:175], v[48:51]
	v_mfma_f32_16x16x32_bf16 v[44:47], v[124:127], v[172:175], v[44:47]
	v_mfma_f32_16x16x32_bf16 v[32:35], v[108:111], v[180:183], v[32:35]
	v_mfma_f32_16x16x32_bf16 v[28:31], v[124:127], v[180:183], v[28:31]
	v_mfma_f32_16x16x32_bf16 v[16:19], v[108:111], v[188:191], v[16:19]
	v_mfma_f32_16x16x32_bf16 v[12:15], v[124:127], v[188:191], v[12:15]
	v_mfma_f32_16x16x32_bf16 v[64:67], v[112:115], v[168:171], v[64:67]
	v_mfma_f32_16x16x32_bf16 v[60:63], v[128:131], v[168:171], v[60:63]
	v_mfma_f32_16x16x32_bf16 v[48:51], v[112:115], v[176:179], v[48:51]
	v_mfma_f32_16x16x32_bf16 v[44:47], v[128:131], v[176:179], v[44:47]
	v_mfma_f32_16x16x32_bf16 v[32:35], v[112:115], v[184:187], v[32:35]
	v_mfma_f32_16x16x32_bf16 v[28:31], v[128:131], v[184:187], v[28:31]
	v_mfma_f32_16x16x32_bf16 v[16:19], v[112:115], v[192:195], v[16:19]
	v_mfma_f32_16x16x32_bf16 v[12:15], v[128:131], v[192:195], v[12:15]
	s_setprio 0
	s_setprio 1
	v_mfma_f32_16x16x32_bf16 v[56:59], v[132:135], v[164:167], v[56:59]
	v_mfma_f32_16x16x32_bf16 v[52:55], v[148:151], v[164:167], v[52:55]
	v_mfma_f32_16x16x32_bf16 v[40:43], v[132:135], v[172:175], v[40:43]
	v_mfma_f32_16x16x32_bf16 v[36:39], v[148:151], v[172:175], v[36:39]
	v_mfma_f32_16x16x32_bf16 v[24:27], v[132:135], v[180:183], v[24:27]
	v_mfma_f32_16x16x32_bf16 v[20:23], v[148:151], v[180:183], v[20:23]
	v_mfma_f32_16x16x32_bf16 v[8:11], v[132:135], v[188:191], v[8:11]
	v_mfma_f32_16x16x32_bf16 v[4:7], v[148:151], v[188:191], v[4:7]
	v_mfma_f32_16x16x32_bf16 v[56:59], v[140:143], v[168:171], v[56:59]
	v_mfma_f32_16x16x32_bf16 v[52:55], v[156:159], v[168:171], v[52:55]
	v_mfma_f32_16x16x32_bf16 v[40:43], v[140:143], v[176:179], v[40:43]
	v_mfma_f32_16x16x32_bf16 v[36:39], v[156:159], v[176:179], v[36:39]
	v_mfma_f32_16x16x32_bf16 v[24:27], v[140:143], v[184:187], v[24:27]
	v_mfma_f32_16x16x32_bf16 v[20:23], v[156:159], v[184:187], v[20:23]
	v_mfma_f32_16x16x32_bf16 v[8:11], v[140:143], v[192:195], v[8:11]
	v_mfma_f32_16x16x32_bf16 v[4:7], v[156:159], v[192:195], v[4:7]
	s_setprio 0
	s_barrier
	s_add_i32 s52, 0, 0x18000
	s_add_i32 s53, 0, 0x1c000
	v_add_u32_e32 v128, s52, v251
	v_add_u32_e32 v156, s53, v251
	ds_read_b128 v[108:111], v128
	ds_read_b128 v[112:115], v128 offset:1024
	ds_read_b128 v[124:127], v128 offset:2048
	ds_read_b128 v[128:131], v128 offset:3072
	ds_read_b128 v[132:135], v156
	ds_read_b128 v[140:143], v156 offset:1024
	ds_read_b128 v[148:151], v156 offset:2048
	ds_read_b128 v[156:159], v156 offset:3072
	s_add_u32 s34, s34, 0x40000
	s_addc_u32 s35, s35, 0
	s_mov_b32 m0, s46
	v_lshl_add_u64 v[220:221], s[34:35], 0, v[0:1]
	ds_read_b128 v[164:167], v253 offset:32768
	ds_read_b128 v[168:171], v253 offset:33792
	ds_read_b128 v[172:175], v253 offset:34816
	ds_read_b128 v[176:179], v253 offset:35840
	ds_read_b128 v[180:183], v253 offset:36864
	ds_read_b128 v[184:187], v253 offset:37888
	ds_read_b128 v[188:191], v253 offset:38912
	ds_read_b128 v[192:195], v253 offset:39936
	global_load_lds_dwordx4 v[220:221], off
	s_mov_b32 m0, s47
	v_lshl_add_u64 v[220:221], s[34:35], 0, v[204:205]
	global_load_lds_dwordx4 v[220:221], off
	s_waitcnt vmcnt(8)
	s_waitcnt lgkmcnt(0)
	s_barrier
	s_setprio 1
	s_waitcnt lgkmcnt(0)
	v_mfma_f32_16x16x32_bf16 v[160:163], v[108:111], v[164:167], v[160:163]
	v_mfma_f32_16x16x32_bf16 v[152:155], v[124:127], v[164:167], v[152:155]
	v_mfma_f32_16x16x32_bf16 v[120:123], v[108:111], v[172:175], v[120:123]
	v_mfma_f32_16x16x32_bf16 v[116:119], v[124:127], v[172:175], v[116:119]
	v_mfma_f32_16x16x32_bf16 v[96:99], v[108:111], v[180:183], v[96:99]
	v_mfma_f32_16x16x32_bf16 v[92:95], v[124:127], v[180:183], v[92:95]
	v_mfma_f32_16x16x32_bf16 v[80:83], v[108:111], v[188:191], v[80:83]
	v_mfma_f32_16x16x32_bf16 v[76:79], v[124:127], v[188:191], v[76:79]
	v_mfma_f32_16x16x32_bf16 v[160:163], v[112:115], v[168:171], v[160:163]
	v_mfma_f32_16x16x32_bf16 v[152:155], v[128:131], v[168:171], v[152:155]
	v_mfma_f32_16x16x32_bf16 v[120:123], v[112:115], v[176:179], v[120:123]
	v_mfma_f32_16x16x32_bf16 v[116:119], v[128:131], v[176:179], v[116:119]
	v_mfma_f32_16x16x32_bf16 v[96:99], v[112:115], v[184:187], v[96:99]
	v_mfma_f32_16x16x32_bf16 v[92:95], v[128:131], v[184:187], v[92:95]
	v_mfma_f32_16x16x32_bf16 v[80:83], v[112:115], v[192:195], v[80:83]
	v_mfma_f32_16x16x32_bf16 v[76:79], v[128:131], v[192:195], v[76:79]
	s_setprio 0
	s_setprio 1
	v_mfma_f32_16x16x32_bf16 v[144:147], v[132:135], v[164:167], v[144:147]
	v_mfma_f32_16x16x32_bf16 v[136:139], v[148:151], v[164:167], v[136:139]
	v_mfma_f32_16x16x32_bf16 v[104:107], v[132:135], v[172:175], v[104:107]
	v_mfma_f32_16x16x32_bf16 v[100:103], v[148:151], v[172:175], v[100:103]
	v_mfma_f32_16x16x32_bf16 v[88:91], v[132:135], v[180:183], v[88:91]
	v_mfma_f32_16x16x32_bf16 v[84:87], v[148:151], v[180:183], v[84:87]
	v_mfma_f32_16x16x32_bf16 v[72:75], v[132:135], v[188:191], v[72:75]
	v_mfma_f32_16x16x32_bf16 v[68:71], v[148:151], v[188:191], v[68:71]
	v_mfma_f32_16x16x32_bf16 v[144:147], v[140:143], v[168:171], v[144:147]
	v_mfma_f32_16x16x32_bf16 v[136:139], v[156:159], v[168:171], v[136:139]
	v_mfma_f32_16x16x32_bf16 v[104:107], v[140:143], v[176:179], v[104:107]
	v_mfma_f32_16x16x32_bf16 v[100:103], v[156:159], v[176:179], v[100:103]
	v_mfma_f32_16x16x32_bf16 v[88:91], v[140:143], v[184:187], v[88:91]
	v_mfma_f32_16x16x32_bf16 v[84:87], v[156:159], v[184:187], v[84:87]
	v_mfma_f32_16x16x32_bf16 v[72:75], v[140:143], v[192:195], v[72:75]
	v_mfma_f32_16x16x32_bf16 v[68:71], v[156:159], v[192:195], v[68:71]
	s_setprio 0
	s_barrier
; #define PG8_STAGE(bufoff, gbase, voff) do { _Pragma("unroll") for (int _i = 0; _i < 2; ++_i) \
;         __builtin_amdgcn_global_load_lds((const unsigned*)((const char*)(gbase) + (voff)[_i]), (PG8_LAS unsigned*)(lds + (bufoff) + ldsw + _i * 8192), 16, 0, 0); } while (0)
; #define PG8_LDA(dst, b, h) do { _Pragma("unroll") for (int m = 0; m < 4; ++m) _Pragma("unroll") for (int k = 0; k < 2; ++k) dst[m][k] = *(const PG8_LAS bf16x8*)(lds + PG8_SA(b, h) + aoff + m * 2048 + k * 1024); } while (0)
; #define PG8_MMA(ai, bj, At, Bt) do { __builtin_amdgcn_s_setprio(1); _Pragma("unroll") for (int m = 0; m < 4; ++m) _Pragma("unroll") for (int n = 0; n < 2; ++n) _Pragma("unroll") for (int k = 0; k < 2; ++k) \
;         acc[ai][bj][m][n] = __builtin_amdgcn_mfma_f32_16x16x32_bf16(Bt[n][k], At[m][k], acc[ai][bj][m][n], 0, 0, 0); __builtin_amdgcn_s_setprio(0); } while (0)
; #define PG8_WAIT_V(n) asm volatile("s_waitcnt vmcnt(" #n ")" ::: "memory")
; #define PG8_WAIT_L(n) asm volatile("s_waitcnt lgkmcnt(" #n ")" ::: "memory")
; #define PG8_BAR __builtin_amdgcn_s_barrier()
; #define PG8_SCHED __builtin_amdgcn_sched_barrier(0)
; template <class Epi, class Sched, bool ALIGN_EPI = false, bool SP2 = false>
; __device__ __forceinline__ void gemm_phase(PG8_LAS unsigned char* lds, const Gemm g, const Sched& S, const Epi& E) {
;     ...
;             PG8_LDA(At, 1, 1); PG8_STAGE(PG8_SB(1, 0), b3, voffB); PG8_STAGE(PG8_SB(1, 1), b3 + hstep, voffB); PG8_STAGE(PG8_SA(1, 0), a3, voffA);
;             PG8_WAIT_V(8); PG8_WAIT_L(0); PG8_BAR; PG8_MMA(1, 0, At, B0); PG8_MMA(1, 1, At, B1); PG8_BAR; PG8_SCHED;
;     ...
;         if constexpr (ALIGN_EPI) { if (wr == 0) PG8_BAR; }
	s_add_i32 s34, s52, s41
	v_lshl_add_u64 v[212:213], v[212:213], 0, s[82:83]
	s_mov_b32 m0, s34
	ds_read_b128 v[164:167], v253 offset:49152
	ds_read_b128 v[168:171], v253 offset:50176
	ds_read_b128 v[172:175], v253 offset:51200
	ds_read_b128 v[176:179], v253 offset:52224
	ds_read_b128 v[180:183], v253 offset:53248
	ds_read_b128 v[184:187], v253 offset:54272
	ds_read_b128 v[188:191], v253 offset:55296
	ds_read_b128 v[192:195], v253 offset:56320
	global_load_lds_dwordx4 v[212:213], off
	s_add_i32 m0, s34, 0x2000
	s_add_u32 s30, s30, 0x40080
	v_lshl_add_u64 v[212:213], v[214:215], 0, s[82:83]
	s_addc_u32 s31, s31, 0
	s_add_i32 s34, s53, s41
	global_load_lds_dwordx4 v[212:213], off
	s_mov_b32 m0, s34
	v_lshl_add_u64 v[212:213], s[30:31], 0, v[202:203]
	global_load_lds_dwordx4 v[212:213], off
	s_add_i32 m0, s34, 0x2000
	v_lshl_add_u64 v[212:213], s[30:31], 0, v[206:207]
	global_load_lds_dwordx4 v[212:213], off
	s_mov_b32 m0, s49
	v_lshl_add_u64 v[212:213], v[216:217], 0, s[82:83]
	global_load_lds_dwordx4 v[212:213], off
	s_mov_b32 m0, s50
	v_lshl_add_u64 v[212:213], v[218:219], 0, s[82:83]
	global_load_lds_dwordx4 v[212:213], off
	s_waitcnt vmcnt(8)
	s_waitcnt lgkmcnt(0)
	s_barrier
	s_setprio 1
	s_waitcnt lgkmcnt(0)
	v_mfma_f32_16x16x32_bf16 v[64:67], v[108:111], v[164:167], v[64:67]
	v_mfma_f32_16x16x32_bf16 v[60:63], v[124:127], v[164:167], v[60:63]
	v_mfma_f32_16x16x32_bf16 v[48:51], v[108:111], v[172:175], v[48:51]
	v_mfma_f32_16x16x32_bf16 v[44:47], v[124:127], v[172:175], v[44:47]
	v_mfma_f32_16x16x32_bf16 v[32:35], v[108:111], v[180:183], v[32:35]
	v_mfma_f32_16x16x32_bf16 v[28:31], v[124:127], v[180:183], v[28:31]
	v_mfma_f32_16x16x32_bf16 v[16:19], v[108:111], v[188:191], v[16:19]
	v_mfma_f32_16x16x32_bf16 v[12:15], v[124:127], v[188:191], v[12:15]
	v_mfma_f32_16x16x32_bf16 v[64:67], v[112:115], v[168:171], v[64:67]
	v_mfma_f32_16x16x32_bf16 v[60:63], v[128:131], v[168:171], v[60:63]
	v_mfma_f32_16x16x32_bf16 v[48:51], v[112:115], v[176:179], v[48:51]
	v_mfma_f32_16x16x32_bf16 v[44:47], v[128:131], v[176:179], v[44:47]
	v_mfma_f32_16x16x32_bf16 v[32:35], v[112:115], v[184:187], v[32:35]
	v_mfma_f32_16x16x32_bf16 v[28:31], v[128:131], v[184:187], v[28:31]
	v_mfma_f32_16x16x32_bf16 v[16:19], v[112:115], v[192:195], v[16:19]
	v_mfma_f32_16x16x32_bf16 v[12:15], v[128:131], v[192:195], v[12:15]
	s_setprio 0
	s_setprio 1
	v_mfma_f32_16x16x32_bf16 v[56:59], v[132:135], v[164:167], v[56:59]
	v_mfma_f32_16x16x32_bf16 v[52:55], v[148:151], v[164:167], v[52:55]
	v_mfma_f32_16x16x32_bf16 v[40:43], v[132:135], v[172:175], v[40:43]
	v_mfma_f32_16x16x32_bf16 v[36:39], v[148:151], v[172:175], v[36:39]
	v_mfma_f32_16x16x32_bf16 v[24:27], v[132:135], v[180:183], v[24:27]
	v_mfma_f32_16x16x32_bf16 v[20:23], v[148:151], v[180:183], v[20:23]
	v_mfma_f32_16x16x32_bf16 v[8:11], v[132:135], v[188:191], v[8:11]
	v_mfma_f32_16x16x32_bf16 v[4:7], v[148:151], v[188:191], v[4:7]
	v_mfma_f32_16x16x32_bf16 v[56:59], v[140:143], v[168:171], v[56:59]
	v_mfma_f32_16x16x32_bf16 v[52:55], v[156:159], v[168:171], v[52:55]
	v_mfma_f32_16x16x32_bf16 v[40:43], v[140:143], v[176:179], v[40:43]
	v_mfma_f32_16x16x32_bf16 v[36:39], v[156:159], v[176:179], v[36:39]
	v_mfma_f32_16x16x32_bf16 v[24:27], v[140:143], v[184:187], v[24:27]
	v_mfma_f32_16x16x32_bf16 v[20:23], v[156:159], v[184:187], v[20:23]
	v_mfma_f32_16x16x32_bf16 v[8:11], v[140:143], v[192:195], v[8:11]
	v_mfma_f32_16x16x32_bf16 v[4:7], v[156:159], v[192:195], v[4:7]
	s_setprio 0
	s_barrier
	s_add_i32 s45, s45, 2
	s_add_u32 s28, s28, 0x100
	s_addc_u32 s29, s29, 0
	s_add_u32 s27, s27, 0x100
	s_addc_u32 s44, s44, 0
	s_cmp_gt_u32 s45, 13
	s_cbranch_scc0 .LBB0_329
	s_and_b64 vcc, exec, s[14:15]
	s_cbranch_vccz .LBB0_332
	s_barrier

; #define PG8_STAGE(bufoff, gbase, voff) do { _Pragma("unroll") for (int _i = 0; _i < 2; ++_i) \
;         __builtin_amdgcn_global_load_lds((const unsigned*)((const char*)(gbase) + (voff)[_i]), (PG8_LAS unsigned*)(lds + (bufoff) + ldsw + _i * 8192), 16, 0, 0); } while (0)
; #define PG8_LDA(dst, b, h) do { _Pragma("unroll") for (int m = 0; m < 4; ++m) _Pragma("unroll") for (int k = 0; k < 2; ++k) dst[m][k] = *(const PG8_LAS bf16x8*)(lds + PG8_SA(b, h) + aoff + m * 2048 + k * 1024); } while (0)
; #define PG8_LDB(dst, b, h) do { _Pragma("unroll") for (int n = 0; n < 2; ++n) _Pragma("unroll") for (int k = 0; k < 2; ++k) dst[n][k] = *(const PG8_LAS bf16x8*)(lds + PG8_SB(b, h) + boff + n * 2048 + k * 1024); } while (0)
; #define PG8_MMA(ai, bj, At, Bt) do { __builtin_amdgcn_s_setprio(1); _Pragma("unroll") for (int m = 0; m < 4; ++m) _Pragma("unroll") for (int n = 0; n < 2; ++n) _Pragma("unroll") for (int k = 0; k < 2; ++k) \
;         acc[ai][bj][m][n] = __builtin_amdgcn_mfma_f32_16x16x32_bf16(Bt[n][k], At[m][k], acc[ai][bj][m][n], 0, 0, 0); __builtin_amdgcn_s_setprio(0); } while (0)
; #define PG8_WAIT_V(n) asm volatile("s_waitcnt vmcnt(" #n ")" ::: "memory")
; #define PG8_BAR __builtin_amdgcn_s_barrier()
; template <class Epi, class Sched, bool ALIGN_EPI = false, bool SP2 = false>
; __device__ __forceinline__ void gemm_phase(PG8_LAS unsigned char* lds, const Gemm g, const Sched& S, const Epi& E) {
;     ...
;         for (int t = 0; t < nt; t += 2) {
;             const bool last = (t == nt - 2);
;             const char* a1 = cA + (size_t)(t + 1) * kstep;
;             const char* a2 = last ? nA : cA + (size_t)(t + 2) * kstep; const char* b2 = last ? nB : cB + (size_t)(t + 2) * kstep;
;             const char* a3 = a2 + kstep; const char* b3 = b2 + kstep;
;             if (last && has_next) S.a_ready(nxt);
;             if constexpr (SP2) {
;             PG8_LDB(B0, 0, 0); PG8_LDB(B1, 0, 1); PG8_SCHED; PG8_LDA(At, 0, 0); PG8_STAGE(PG8_SA(1, 1), a1 + hstep, voffA);
;             PG8_WAIT_V(8); PG8_WAIT_L(0); PG8_BAR; PG8_MMA(0, 0, At, B0); PG8_MMA(0, 1, At, B1); PG8_BAR; PG8_SCHED;
;             PG8_LDA(At, 0, 1); PG8_STAGE(PG8_SB(0, 0), b2, voffB); PG8_STAGE(PG8_SB(0, 1), b2 + hstep, voffB); PG8_STAGE(PG8_SA(0, 0), a2, voffA);
;             PG8_WAIT_V(8); PG8_WAIT_L(0); PG8_BAR; PG8_MMA(1, 0, At, B0); PG8_MMA(1, 1, At, B1); PG8_BAR; PG8_SCHED;
.LBB0_405:
	s_add_u32 s24, s8, 0xfffc0080
	s_addc_u32 s25, s9, -1
	s_add_i32 s47, 0, 0x10000
	s_cmp_eq_u32 s46, 12
	s_cselect_b32 s27, s7, s25
	s_cselect_b32 s26, s17, s24
	s_cselect_b32 s25, s19, s45
	s_cselect_b32 s24, s43, s44
	s_add_i32 s50, 0, 0x14000
	v_add_u32_e32 v156, s47, v164
	v_add_u32_e32 v167, s50, v164
	ds_read_b128 v[144:147], v156
	ds_read_b128 v[148:151], v156 offset:1024
	ds_read_b128 v[152:155], v156 offset:2048
	ds_read_b128 v[156:159], v156 offset:3072
	ds_read_b128 v[160:163], v167
	ds_read_b128 v[168:171], v167 offset:1024
	ds_read_b128 v[172:175], v167 offset:2048
	ds_read_b128 v[176:179], v167 offset:3072
	v_lshl_add_u64 v[198:199], s[8:9], 0, v[140:141]
	s_add_i32 m0, s37, 0xc000
	ds_read_b128 v[180:183], v166
	ds_read_b128 v[184:187], v166 offset:1024
	ds_read_b128 v[188:191], v166 offset:2048
	ds_read_b128 v[192:195], v166 offset:3072
	ds_read_b128 v[202:205], v166 offset:4096
	ds_read_b128 v[206:209], v166 offset:5120
	ds_read_b128 v[210:213], v166 offset:6144
	ds_read_b128 v[214:217], v166 offset:7168
	global_load_lds_dwordx4 v[198:199], off
	s_add_i32 m0, s37, 0xe000
	v_lshl_add_u64 v[198:199], s[8:9], 0, v[142:143]
	global_load_lds_dwordx4 v[198:199], off
	s_waitcnt vmcnt(8)
	s_waitcnt lgkmcnt(0)
	s_barrier
	s_setprio 1
	s_waitcnt lgkmcnt(0)
	v_mfma_f32_16x16x32_bf16 v[128:131], v[144:147], v[180:183], v[128:131]
	v_mfma_f32_16x16x32_bf16 v[120:123], v[152:155], v[180:183], v[120:123]
	v_mfma_f32_16x16x32_bf16 v[112:115], v[144:147], v[188:191], v[112:115]
	v_mfma_f32_16x16x32_bf16 v[104:107], v[152:155], v[188:191], v[104:107]
	v_mfma_f32_16x16x32_bf16 v[96:99], v[144:147], v[202:205], v[96:99]
	v_mfma_f32_16x16x32_bf16 v[88:91], v[152:155], v[202:205], v[88:91]
	v_mfma_f32_16x16x32_bf16 v[80:83], v[144:147], v[210:213], v[80:83]
	v_mfma_f32_16x16x32_bf16 v[72:75], v[152:155], v[210:213], v[72:75]
	v_mfma_f32_16x16x32_bf16 v[128:131], v[148:151], v[184:187], v[128:131]
	v_mfma_f32_16x16x32_bf16 v[120:123], v[156:159], v[184:187], v[120:123]
	v_mfma_f32_16x16x32_bf16 v[112:115], v[148:151], v[192:195], v[112:115]
	v_mfma_f32_16x16x32_bf16 v[104:107], v[156:159], v[192:195], v[104:107]
	v_mfma_f32_16x16x32_bf16 v[96:99], v[148:151], v[206:209], v[96:99]
	v_mfma_f32_16x16x32_bf16 v[88:91], v[156:159], v[206:209], v[88:91]
	v_mfma_f32_16x16x32_bf16 v[80:83], v[148:151], v[214:217], v[80:83]
	v_mfma_f32_16x16x32_bf16 v[72:75], v[156:159], v[214:217], v[72:75]
	s_setprio 0
	s_setprio 1
	v_mfma_f32_16x16x32_bf16 v[124:127], v[160:163], v[180:183], v[124:127]
	v_mfma_f32_16x16x32_bf16 v[116:119], v[172:175], v[180:183], v[116:119]
	v_mfma_f32_16x16x32_bf16 v[108:111], v[160:163], v[188:191], v[108:111]
	v_mfma_f32_16x16x32_bf16 v[100:103], v[172:175], v[188:191], v[100:103]
	v_mfma_f32_16x16x32_bf16 v[92:95], v[160:163], v[202:205], v[92:95]
	v_mfma_f32_16x16x32_bf16 v[84:87], v[172:175], v[202:205], v[84:87]
	v_mfma_f32_16x16x32_bf16 v[76:79], v[160:163], v[210:213], v[76:79]
	v_mfma_f32_16x16x32_bf16 v[68:71], v[172:175], v[210:213], v[68:71]
	v_mfma_f32_16x16x32_bf16 v[124:127], v[168:171], v[184:187], v[124:127]
	v_mfma_f32_16x16x32_bf16 v[116:119], v[176:179], v[184:187], v[116:119]
	v_mfma_f32_16x16x32_bf16 v[108:111], v[168:171], v[192:195], v[108:111]
	v_mfma_f32_16x16x32_bf16 v[100:103], v[176:179], v[192:195], v[100:103]
	v_mfma_f32_16x16x32_bf16 v[92:95], v[168:171], v[206:209], v[92:95]
	v_mfma_f32_16x16x32_bf16 v[84:87], v[176:179], v[206:209], v[84:87]
	v_mfma_f32_16x16x32_bf16 v[76:79], v[168:171], v[214:217], v[76:79]
	v_mfma_f32_16x16x32_bf16 v[68:71], v[176:179], v[214:217], v[68:71]
	s_setprio 0
	s_barrier
	s_add_i32 s47, s47, s35
	v_lshl_add_u64 v[198:199], s[24:25], 0, v[134:135]
	s_mov_b32 m0, s47
	ds_read_b128 v[180:183], v166 offset:16384
	ds_read_b128 v[184:187], v166 offset:17408
	ds_read_b128 v[188:191], v166 offset:18432
	ds_read_b128 v[192:195], v166 offset:19456
	ds_read_b128 v[202:205], v166 offset:20480
	ds_read_b128 v[206:209], v166 offset:21504
	ds_read_b128 v[210:213], v166 offset:22528
	ds_read_b128 v[214:217], v166 offset:23552
	global_load_lds_dwordx4 v[198:199], off
	s_add_i32 m0, s47, 0x2000
	s_add_u32 s48, s24, 0x40000
	v_lshl_add_u64 v[218:219], s[24:25], 0, v[0:1]
	s_addc_u32 s49, s25, 0
	s_add_i32 s47, s50, s35
	global_load_lds_dwordx4 v[218:219], off
	v_lshl_add_u64 v[220:221], s[48:49], 0, v[134:135]
	s_mov_b32 m0, s47
	v_lshl_add_u64 v[222:223], s[26:27], 0, v[132:133]
	global_load_lds_dwordx4 v[220:221], off
	s_add_i32 m0, s47, 0x2000
	v_lshl_add_u64 v[220:221], s[48:49], 0, v[0:1]
	global_load_lds_dwordx4 v[220:221], off
	s_mov_b32 m0, s37
	v_lshl_add_u64 v[220:221], s[26:27], 0, v[136:137]
	global_load_lds_dwordx4 v[220:221], off
	s_mov_b32 m0, s38
	s_nop 0
	global_load_lds_dwordx4 v[222:223], off
	s_waitcnt vmcnt(8)
	s_waitcnt lgkmcnt(0)
	s_barrier
; #define PG8_STAGE(bufoff, gbase, voff) do { _Pragma("unroll") for (int _i = 0; _i < 2; ++_i) \
;         __builtin_amdgcn_global_load_lds((const unsigned*)((const char*)(gbase) + (voff)[_i]), (PG8_LAS unsigned*)(lds + (bufoff) + ldsw + _i * 8192), 16, 0, 0); } while (0)
; #define PG8_LDA(dst, b, h) do { _Pragma("unroll") for (int m = 0; m < 4; ++m) _Pragma("unroll") for (int k = 0; k < 2; ++k) dst[m][k] = *(const PG8_LAS bf16x8*)(lds + PG8_SA(b, h) + aoff + m * 2048 + k * 1024); } while (0)
; #define PG8_LDB(dst, b, h) do { _Pragma("unroll") for (int n = 0; n < 2; ++n) _Pragma("unroll") for (int k = 0; k < 2; ++k) dst[n][k] = *(const PG8_LAS bf16x8*)(lds + PG8_SB(b, h) + boff + n * 2048 + k * 1024); } while (0)
; #define PG8_MMA(ai, bj, At, Bt) do { __builtin_amdgcn_s_setprio(1); _Pragma("unroll") for (int m = 0; m < 4; ++m) _Pragma("unroll") for (int n = 0; n < 2; ++n) _Pragma("unroll") for (int k = 0; k < 2; ++k) \
;         acc[ai][bj][m][n] = __builtin_amdgcn_mfma_f32_16x16x32_bf16(Bt[n][k], At[m][k], acc[ai][bj][m][n], 0, 0, 0); __builtin_amdgcn_s_setprio(0); } while (0)
; #define PG8_WAIT_V(n) asm volatile("s_waitcnt vmcnt(" #n ")" ::: "memory")
; #define PG8_WAIT_L(n) asm volatile("s_waitcnt lgkmcnt(" #n ")" ::: "memory")
; #define PG8_BAR __builtin_amdgcn_s_barrier()
; #define PG8_SCHED __builtin_amdgcn_sched_barrier(0)
; template <class Epi, class Sched, bool ALIGN_EPI = false, bool SP2 = false>
; __device__ __forceinline__ void gemm_phase(PG8_LAS unsigned char* lds, const Gemm g, const Sched& S, const Epi& E) {
;     ...
;             PG8_WAIT_V(8); PG8_WAIT_L(0); PG8_BAR; PG8_MMA(1, 0, At, B0); PG8_MMA(1, 1, At, B1); PG8_BAR; PG8_SCHED;
;             PG8_LDB(B0, 1, 0); PG8_LDB(B1, 1, 1); PG8_SCHED; PG8_LDA(At, 1, 0); PG8_STAGE(PG8_SA(0, 1), a2 + hstep, voffA);
;             PG8_WAIT_V(8); PG8_WAIT_L(0); PG8_BAR; PG8_MMA(0, 0, At, B0); PG8_MMA(0, 1, At, B1); PG8_BAR; PG8_SCHED;
	s_setprio 1
	s_waitcnt lgkmcnt(0)
	v_mfma_f32_16x16x32_bf16 v[64:67], v[144:147], v[180:183], v[64:67]
	v_mfma_f32_16x16x32_bf16 v[56:59], v[152:155], v[180:183], v[56:59]
	v_mfma_f32_16x16x32_bf16 v[48:51], v[144:147], v[188:191], v[48:51]
	v_mfma_f32_16x16x32_bf16 v[40:43], v[152:155], v[188:191], v[40:43]
	v_mfma_f32_16x16x32_bf16 v[32:35], v[144:147], v[202:205], v[32:35]
	v_mfma_f32_16x16x32_bf16 v[24:27], v[152:155], v[202:205], v[24:27]
	v_mfma_f32_16x16x32_bf16 v[16:19], v[144:147], v[210:213], v[16:19]
	v_mfma_f32_16x16x32_bf16 v[8:11], v[152:155], v[210:213], v[8:11]
	v_mfma_f32_16x16x32_bf16 v[64:67], v[148:151], v[184:187], v[64:67]
	v_mfma_f32_16x16x32_bf16 v[56:59], v[156:159], v[184:187], v[56:59]
	v_mfma_f32_16x16x32_bf16 v[48:51], v[148:151], v[192:195], v[48:51]
	v_mfma_f32_16x16x32_bf16 v[40:43], v[156:159], v[192:195], v[40:43]
	v_mfma_f32_16x16x32_bf16 v[32:35], v[148:151], v[206:209], v[32:35]
	v_mfma_f32_16x16x32_bf16 v[24:27], v[156:159], v[206:209], v[24:27]
	v_mfma_f32_16x16x32_bf16 v[16:19], v[148:151], v[214:217], v[16:19]
	v_mfma_f32_16x16x32_bf16 v[8:11], v[156:159], v[214:217], v[8:11]
	s_setprio 0
	s_setprio 1
	v_mfma_f32_16x16x32_bf16 v[60:63], v[160:163], v[180:183], v[60:63]
	v_mfma_f32_16x16x32_bf16 v[52:55], v[172:175], v[180:183], v[52:55]
	v_mfma_f32_16x16x32_bf16 v[44:47], v[160:163], v[188:191], v[44:47]
	v_mfma_f32_16x16x32_bf16 v[36:39], v[172:175], v[188:191], v[36:39]
	v_mfma_f32_16x16x32_bf16 v[28:31], v[160:163], v[202:205], v[28:31]
	v_mfma_f32_16x16x32_bf16 v[20:23], v[172:175], v[202:205], v[20:23]
	v_mfma_f32_16x16x32_bf16 v[12:15], v[160:163], v[210:213], v[12:15]
	v_mfma_f32_16x16x32_bf16 v[4:7], v[172:175], v[210:213], v[4:7]
	v_mfma_f32_16x16x32_bf16 v[60:63], v[168:171], v[184:187], v[60:63]
	v_mfma_f32_16x16x32_bf16 v[52:55], v[176:179], v[184:187], v[52:55]
	v_mfma_f32_16x16x32_bf16 v[44:47], v[168:171], v[192:195], v[44:47]
	v_mfma_f32_16x16x32_bf16 v[36:39], v[176:179], v[192:195], v[36:39]
	v_mfma_f32_16x16x32_bf16 v[28:31], v[168:171], v[206:209], v[28:31]
	v_mfma_f32_16x16x32_bf16 v[20:23], v[176:179], v[206:209], v[20:23]
	v_mfma_f32_16x16x32_bf16 v[12:15], v[168:171], v[214:217], v[12:15]
	v_mfma_f32_16x16x32_bf16 v[4:7], v[176:179], v[214:217], v[4:7]
	s_setprio 0
	s_barrier
	s_add_i32 s47, 0, 0x18000
	s_add_i32 s48, 0, 0x1c000
	v_add_u32_e32 v156, s47, v164
	v_add_u32_e32 v167, s48, v164
	ds_read_b128 v[144:147], v156
	ds_read_b128 v[148:151], v156 offset:1024
	ds_read_b128 v[152:155], v156 offset:2048
	ds_read_b128 v[156:159], v156 offset:3072
	ds_read_b128 v[160:163], v167
	ds_read_b128 v[168:171], v167 offset:1024
	ds_read_b128 v[172:175], v167 offset:2048
	ds_read_b128 v[176:179], v167 offset:3072
	s_add_u32 s26, s26, 0x40000
	s_addc_u32 s27, s27, 0
	s_mov_b32 m0, s39
	v_lshl_add_u64 v[224:225], s[26:27], 0, v[136:137]
	ds_read_b128 v[180:183], v166 offset:32768
	ds_read_b128 v[184:187], v166 offset:33792
	ds_read_b128 v[188:191], v166 offset:34816
	ds_read_b128 v[192:195], v166 offset:35840
	ds_read_b128 v[202:205], v166 offset:36864
	ds_read_b128 v[206:209], v166 offset:37888
	ds_read_b128 v[210:213], v166 offset:38912
	ds_read_b128 v[214:217], v166 offset:39936
	global_load_lds_dwordx4 v[224:225], off
	s_mov_b32 m0, s40
	v_lshl_add_u64 v[224:225], s[26:27], 0, v[132:133]
	global_load_lds_dwordx4 v[224:225], off
	s_waitcnt vmcnt(8)
	s_waitcnt lgkmcnt(0)
	s_barrier
	s_setprio 1
	s_waitcnt lgkmcnt(0)
	v_mfma_f32_16x16x32_bf16 v[128:131], v[144:147], v[180:183], v[128:131]
	v_mfma_f32_16x16x32_bf16 v[120:123], v[152:155], v[180:183], v[120:123]
	v_mfma_f32_16x16x32_bf16 v[112:115], v[144:147], v[188:191], v[112:115]
	v_mfma_f32_16x16x32_bf16 v[104:107], v[152:155], v[188:191], v[104:107]
	v_mfma_f32_16x16x32_bf16 v[96:99], v[144:147], v[202:205], v[96:99]
	v_mfma_f32_16x16x32_bf16 v[88:91], v[152:155], v[202:205], v[88:91]
	v_mfma_f32_16x16x32_bf16 v[80:83], v[144:147], v[210:213], v[80:83]
	v_mfma_f32_16x16x32_bf16 v[72:75], v[152:155], v[210:213], v[72:75]
	v_mfma_f32_16x16x32_bf16 v[128:131], v[148:151], v[184:187], v[128:131]
	v_mfma_f32_16x16x32_bf16 v[120:123], v[156:159], v[184:187], v[120:123]
	v_mfma_f32_16x16x32_bf16 v[112:115], v[148:151], v[192:195], v[112:115]
	v_mfma_f32_16x16x32_bf16 v[104:107], v[156:159], v[192:195], v[104:107]
	v_mfma_f32_16x16x32_bf16 v[96:99], v[148:151], v[206:209], v[96:99]
	v_mfma_f32_16x16x32_bf16 v[88:91], v[156:159], v[206:209], v[88:91]
	v_mfma_f32_16x16x32_bf16 v[80:83], v[148:151], v[214:217], v[80:83]
	v_mfma_f32_16x16x32_bf16 v[72:75], v[156:159], v[214:217], v[72:75]
	s_setprio 0
	s_setprio 1
	v_mfma_f32_16x16x32_bf16 v[124:127], v[160:163], v[180:183], v[124:127]
	v_mfma_f32_16x16x32_bf16 v[116:119], v[172:175], v[180:183], v[116:119]
	v_mfma_f32_16x16x32_bf16 v[108:111], v[160:163], v[188:191], v[108:111]
	v_mfma_f32_16x16x32_bf16 v[100:103], v[172:175], v[188:191], v[100:103]
	v_mfma_f32_16x16x32_bf16 v[92:95], v[160:163], v[202:205], v[92:95]
	v_mfma_f32_16x16x32_bf16 v[84:87], v[172:175], v[202:205], v[84:87]
	v_mfma_f32_16x16x32_bf16 v[76:79], v[160:163], v[210:213], v[76:79]
	v_mfma_f32_16x16x32_bf16 v[68:71], v[172:175], v[210:213], v[68:71]
	v_mfma_f32_16x16x32_bf16 v[124:127], v[168:171], v[184:187], v[124:127]
	v_mfma_f32_16x16x32_bf16 v[116:119], v[176:179], v[184:187], v[116:119]
	v_mfma_f32_16x16x32_bf16 v[108:111], v[168:171], v[192:195], v[108:111]
	v_mfma_f32_16x16x32_bf16 v[100:103], v[176:179], v[192:195], v[100:103]
	v_mfma_f32_16x16x32_bf16 v[92:95], v[168:171], v[206:209], v[92:95]
	v_mfma_f32_16x16x32_bf16 v[84:87], v[176:179], v[206:209], v[84:87]
	v_mfma_f32_16x16x32_bf16 v[76:79], v[168:171], v[214:217], v[76:79]
	v_mfma_f32_16x16x32_bf16 v[68:71], v[176:179], v[214:217], v[68:71]
	s_setprio 0
	s_barrier
; #define PG8_STAGE(bufoff, gbase, voff) do { _Pragma("unroll") for (int _i = 0; _i < 2; ++_i) \
;         __builtin_amdgcn_global_load_lds((const unsigned*)((const char*)(gbase) + (voff)[_i]), (PG8_LAS unsigned*)(lds + (bufoff) + ldsw + _i * 8192), 16, 0, 0); } while (0)
; #define PG8_LDA(dst, b, h) do { _Pragma("unroll") for (int m = 0; m < 4; ++m) _Pragma("unroll") for (int k = 0; k < 2; ++k) dst[m][k] = *(const PG8_LAS bf16x8*)(lds + PG8_SA(b, h) + aoff + m * 2048 + k * 1024); } while (0)
; #define PG8_MMA(ai, bj, At, Bt) do { __builtin_amdgcn_s_setprio(1); _Pragma("unroll") for (int m = 0; m < 4; ++m) _Pragma("unroll") for (int n = 0; n < 2; ++n) _Pragma("unroll") for (int k = 0; k < 2; ++k) \
;         acc[ai][bj][m][n] = __builtin_amdgcn_mfma_f32_16x16x32_bf16(Bt[n][k], At[m][k], acc[ai][bj][m][n], 0, 0, 0); __builtin_amdgcn_s_setprio(0); } while (0)
; #define PG8_WAIT_V(n) asm volatile("s_waitcnt vmcnt(" #n ")" ::: "memory")
; #define PG8_WAIT_L(n) asm volatile("s_waitcnt lgkmcnt(" #n ")" ::: "memory")
; #define PG8_BAR __builtin_amdgcn_s_barrier()
; #define PG8_SCHED __builtin_amdgcn_sched_barrier(0)
; template <class Epi, class Sched, bool ALIGN_EPI = false, bool SP2 = false>
; __device__ __forceinline__ void gemm_phase(PG8_LAS unsigned char* lds, const Gemm g, const Sched& S, const Epi& E) {
;     ...
;             PG8_LDA(At, 1, 1); PG8_STAGE(PG8_SB(1, 0), b3, voffB); PG8_STAGE(PG8_SB(1, 1), b3 + hstep, voffB); PG8_STAGE(PG8_SA(1, 0), a3, voffA);
;             PG8_WAIT_V(8); PG8_WAIT_L(0); PG8_BAR; PG8_MMA(1, 0, At, B0); PG8_MMA(1, 1, At, B1); PG8_BAR; PG8_SCHED;
;     ...
;         if constexpr (ALIGN_EPI) { if (wr == 0) PG8_BAR; }
	s_add_i32 s26, s47, s35
	v_lshl_add_u64 v[198:199], v[198:199], 0, s[82:83]
	s_mov_b32 m0, s26
	ds_read_b128 v[180:183], v166 offset:49152
	ds_read_b128 v[184:187], v166 offset:50176
	ds_read_b128 v[188:191], v166 offset:51200
	ds_read_b128 v[192:195], v166 offset:52224
	ds_read_b128 v[202:205], v166 offset:53248
	ds_read_b128 v[206:209], v166 offset:54272
	ds_read_b128 v[210:213], v166 offset:55296
	ds_read_b128 v[214:217], v166 offset:56320
	global_load_lds_dwordx4 v[198:199], off
	s_add_i32 m0, s26, 0x2000
	s_add_u32 s24, s24, 0x40080
	v_lshl_add_u64 v[198:199], v[218:219], 0, s[82:83]
	s_addc_u32 s25, s25, 0
	s_add_i32 s26, s48, s35
	global_load_lds_dwordx4 v[198:199], off
	s_mov_b32 m0, s26
	v_lshl_add_u64 v[198:199], s[24:25], 0, v[134:135]
	global_load_lds_dwordx4 v[198:199], off
	s_add_i32 m0, s26, 0x2000
	v_lshl_add_u64 v[198:199], s[24:25], 0, v[0:1]
	global_load_lds_dwordx4 v[198:199], off
	s_mov_b32 m0, s41
	v_lshl_add_u64 v[198:199], v[220:221], 0, s[82:83]
	global_load_lds_dwordx4 v[198:199], off
	s_mov_b32 m0, s42
	v_lshl_add_u64 v[198:199], v[222:223], 0, s[82:83]
	global_load_lds_dwordx4 v[198:199], off
	s_waitcnt vmcnt(8)
	s_waitcnt lgkmcnt(0)
	s_barrier
	s_setprio 1
	s_waitcnt lgkmcnt(0)
	v_mfma_f32_16x16x32_bf16 v[64:67], v[144:147], v[180:183], v[64:67]
	v_mfma_f32_16x16x32_bf16 v[56:59], v[152:155], v[180:183], v[56:59]
	v_mfma_f32_16x16x32_bf16 v[48:51], v[144:147], v[188:191], v[48:51]
	v_mfma_f32_16x16x32_bf16 v[40:43], v[152:155], v[188:191], v[40:43]
	v_mfma_f32_16x16x32_bf16 v[32:35], v[144:147], v[202:205], v[32:35]
	v_mfma_f32_16x16x32_bf16 v[24:27], v[152:155], v[202:205], v[24:27]
	v_mfma_f32_16x16x32_bf16 v[16:19], v[144:147], v[210:213], v[16:19]
	v_mfma_f32_16x16x32_bf16 v[8:11], v[152:155], v[210:213], v[8:11]
	v_mfma_f32_16x16x32_bf16 v[64:67], v[148:151], v[184:187], v[64:67]
	v_mfma_f32_16x16x32_bf16 v[56:59], v[156:159], v[184:187], v[56:59]
	v_mfma_f32_16x16x32_bf16 v[48:51], v[148:151], v[192:195], v[48:51]
	v_mfma_f32_16x16x32_bf16 v[40:43], v[156:159], v[192:195], v[40:43]
	v_mfma_f32_16x16x32_bf16 v[32:35], v[148:151], v[206:209], v[32:35]
	v_mfma_f32_16x16x32_bf16 v[24:27], v[156:159], v[206:209], v[24:27]
	v_mfma_f32_16x16x32_bf16 v[16:19], v[148:151], v[214:217], v[16:19]
	v_mfma_f32_16x16x32_bf16 v[8:11], v[156:159], v[214:217], v[8:11]
	s_setprio 0
	s_setprio 1
	v_mfma_f32_16x16x32_bf16 v[60:63], v[160:163], v[180:183], v[60:63]
	v_mfma_f32_16x16x32_bf16 v[52:55], v[172:175], v[180:183], v[52:55]
	v_mfma_f32_16x16x32_bf16 v[44:47], v[160:163], v[188:191], v[44:47]
	v_mfma_f32_16x16x32_bf16 v[36:39], v[172:175], v[188:191], v[36:39]
	v_mfma_f32_16x16x32_bf16 v[28:31], v[160:163], v[202:205], v[28:31]
	v_mfma_f32_16x16x32_bf16 v[20:23], v[172:175], v[202:205], v[20:23]
	v_mfma_f32_16x16x32_bf16 v[12:15], v[160:163], v[210:213], v[12:15]
	v_mfma_f32_16x16x32_bf16 v[4:7], v[172:175], v[210:213], v[4:7]
	v_mfma_f32_16x16x32_bf16 v[60:63], v[168:171], v[184:187], v[60:63]
	v_mfma_f32_16x16x32_bf16 v[52:55], v[176:179], v[184:187], v[52:55]
	v_mfma_f32_16x16x32_bf16 v[44:47], v[168:171], v[192:195], v[44:47]
	v_mfma_f32_16x16x32_bf16 v[36:39], v[176:179], v[192:195], v[36:39]
	v_mfma_f32_16x16x32_bf16 v[28:31], v[168:171], v[206:209], v[28:31]
	v_mfma_f32_16x16x32_bf16 v[20:23], v[176:179], v[206:209], v[20:23]
	v_mfma_f32_16x16x32_bf16 v[12:15], v[168:171], v[214:217], v[12:15]
	v_mfma_f32_16x16x32_bf16 v[4:7], v[176:179], v[214:217], v[4:7]
	s_setprio 0
	s_barrier
	s_add_i32 s46, s46, 2
	s_add_u32 s8, s8, 0x100
	s_addc_u32 s9, s9, 0
	s_add_u32 s44, s44, 0x100
	s_addc_u32 s45, s45, 0
	s_cmp_gt_u32 s46, 13
	s_cbranch_scc0 .LBB0_405
	s_and_b64 vcc, exec, s[14:15]
	s_cbranch_vccz .LBB0_408
	s_barrier

; #define PG8_STAGE(bufoff, gbase, voff) do { _Pragma("unroll") for (int _i = 0; _i < 2; ++_i) \
;         __builtin_amdgcn_global_load_lds((const unsigned*)((const char*)(gbase) + (voff)[_i]), (PG8_LAS unsigned*)(lds + (bufoff) + ldsw + _i * 8192), 16, 0, 0); } while (0)
; #define PG8_LDA(dst, b, h) do { _Pragma("unroll") for (int m = 0; m < 4; ++m) _Pragma("unroll") for (int k = 0; k < 2; ++k) dst[m][k] = *(const PG8_LAS bf16x8*)(lds + PG8_SA(b, h) + aoff + m * 2048 + k * 1024); } while (0)
; #define PG8_LDB(dst, b, h) do { _Pragma("unroll") for (int n = 0; n < 2; ++n) _Pragma("unroll") for (int k = 0; k < 2; ++k) dst[n][k] = *(const PG8_LAS bf16x8*)(lds + PG8_SB(b, h) + boff + n * 2048 + k * 1024); } while (0)
; #define PG8_MMA(ai, bj, At, Bt) do { __builtin_amdgcn_s_setprio(1); _Pragma("unroll") for (int m = 0; m < 4; ++m) _Pragma("unroll") for (int n = 0; n < 2; ++n) _Pragma("unroll") for (int k = 0; k < 2; ++k) \
;         acc[ai][bj][m][n] = __builtin_amdgcn_mfma_f32_16x16x32_bf16(Bt[n][k], At[m][k], acc[ai][bj][m][n], 0, 0, 0); __builtin_amdgcn_s_setprio(0); } while (0)
; #define PG8_WAIT_V(n) asm volatile("s_waitcnt vmcnt(" #n ")" ::: "memory")
; #define PG8_BAR __builtin_amdgcn_s_barrier()
; template <class Epi, class Sched, bool ALIGN_EPI = false, bool SP2 = false>
; __device__ __forceinline__ void gemm_phase(PG8_LAS unsigned char* lds, const Gemm g, const Sched& S, const Epi& E) {
;     ...
;         for (int t = 0; t < nt; t += 2) {
;             const bool last = (t == nt - 2);
;             const char* a1 = cA + (size_t)(t + 1) * kstep;
;             const char* a2 = last ? nA : cA + (size_t)(t + 2) * kstep; const char* b2 = last ? nB : cB + (size_t)(t + 2) * kstep;
;             const char* a3 = a2 + kstep; const char* b3 = b2 + kstep;
;             if (last && has_next) S.a_ready(nxt);
;             if constexpr (SP2) {
;             PG8_LDB(B0, 0, 0); PG8_LDB(B1, 0, 1); PG8_SCHED; PG8_LDA(At, 0, 0); PG8_STAGE(PG8_SA(1, 1), a1 + hstep, voffA);
;             PG8_WAIT_V(8); PG8_WAIT_L(0); PG8_BAR; PG8_MMA(0, 0, At, B0); PG8_MMA(0, 1, At, B1); PG8_BAR; PG8_SCHED;
;             PG8_LDA(At, 0, 1); PG8_STAGE(PG8_SB(0, 0), b2, voffB); PG8_STAGE(PG8_SB(0, 1), b2 + hstep, voffB); PG8_STAGE(PG8_SA(0, 0), a2, voffA);
;             PG8_WAIT_V(8); PG8_WAIT_L(0); PG8_BAR; PG8_MMA(1, 0, At, B0); PG8_MMA(1, 1, At, B1); PG8_BAR; PG8_SCHED;
.LBB0_480:
	s_add_u32 s8, s26, 0x100
	s_addc_u32 s9, s27, 0
	s_add_i32 s54, 0, 0x10000
	s_cmp_eq_u32 s53, 40
	s_cselect_b32 s31, s23, s9
	s_cselect_b32 s30, s22, s8
	s_cselect_b32 s29, s25, s45
	s_cselect_b32 s28, s24, s44
	s_add_i32 s55, 0, 0x14000
	v_add_u32_e32 v100, s54, v234
	v_add_u32_e32 v144, s55, v234
	ds_read_b128 v[68:71], v100
	ds_read_b128 v[80:83], v100 offset:1024
	ds_read_b128 v[92:95], v100 offset:2048
	ds_read_b128 v[100:103], v100 offset:3072
	ds_read_b128 v[112:115], v144
	ds_read_b128 v[120:123], v144 offset:1024
	ds_read_b128 v[132:135], v144 offset:2048
	ds_read_b128 v[144:147], v144 offset:3072
	v_lshl_add_u64 v[198:199], s[26:27], 0, v[204:205]
	s_add_i32 m0, s40, 0xc000
	ds_read_b128 v[156:159], v236
	ds_read_b128 v[168:171], v236 offset:1024
	ds_read_b128 v[172:175], v236 offset:2048
	ds_read_b128 v[176:179], v236 offset:3072
	ds_read_b128 v[180:183], v236 offset:4096
	ds_read_b128 v[184:187], v236 offset:5120
	ds_read_b128 v[188:191], v236 offset:6144
	ds_read_b128 v[208:211], v236 offset:7168
	global_load_lds_dwordx4 v[198:199], off
	s_add_i32 m0, s40, 0xe000
	v_lshl_add_u64 v[198:199], s[26:27], 0, v[206:207]
	global_load_lds_dwordx4 v[198:199], off
	s_waitcnt vmcnt(8)
	s_waitcnt lgkmcnt(0)
	s_barrier
	s_setprio 1
	s_waitcnt lgkmcnt(0)
	v_mfma_f32_16x16x32_bf16 v[164:167], v[68:71], v[156:159], v[164:167]
	v_mfma_f32_16x16x32_bf16 v[160:163], v[92:95], v[156:159], v[160:163]
	v_mfma_f32_16x16x32_bf16 v[140:143], v[68:71], v[172:175], v[140:143]
	v_mfma_f32_16x16x32_bf16 v[136:139], v[92:95], v[172:175], v[136:139]
	v_mfma_f32_16x16x32_bf16 v[116:119], v[68:71], v[180:183], v[116:119]
	v_mfma_f32_16x16x32_bf16 v[108:111], v[92:95], v[180:183], v[108:111]
	v_mfma_f32_16x16x32_bf16 v[88:91], v[68:71], v[188:191], v[88:91]
	v_mfma_f32_16x16x32_bf16 v[84:87], v[92:95], v[188:191], v[84:87]
	v_mfma_f32_16x16x32_bf16 v[164:167], v[80:83], v[168:171], v[164:167]
	v_mfma_f32_16x16x32_bf16 v[160:163], v[100:103], v[168:171], v[160:163]
	v_mfma_f32_16x16x32_bf16 v[140:143], v[80:83], v[176:179], v[140:143]
	v_mfma_f32_16x16x32_bf16 v[136:139], v[100:103], v[176:179], v[136:139]
	v_mfma_f32_16x16x32_bf16 v[116:119], v[80:83], v[184:187], v[116:119]
	v_mfma_f32_16x16x32_bf16 v[108:111], v[100:103], v[184:187], v[108:111]
	v_mfma_f32_16x16x32_bf16 v[88:91], v[80:83], v[208:211], v[88:91]
	v_mfma_f32_16x16x32_bf16 v[84:87], v[100:103], v[208:211], v[84:87]
	s_setprio 0
	s_setprio 1
	v_mfma_f32_16x16x32_bf16 v[152:155], v[112:115], v[156:159], v[152:155]
	v_mfma_f32_16x16x32_bf16 v[148:151], v[132:135], v[156:159], v[148:151]
	v_mfma_f32_16x16x32_bf16 v[128:131], v[112:115], v[172:175], v[128:131]
	v_mfma_f32_16x16x32_bf16 v[124:127], v[132:135], v[172:175], v[124:127]
	v_mfma_f32_16x16x32_bf16 v[104:107], v[112:115], v[180:183], v[104:107]
	v_mfma_f32_16x16x32_bf16 v[96:99], v[132:135], v[180:183], v[96:99]
	v_mfma_f32_16x16x32_bf16 v[76:79], v[112:115], v[188:191], v[76:79]
	v_mfma_f32_16x16x32_bf16 v[72:75], v[132:135], v[188:191], v[72:75]
	v_mfma_f32_16x16x32_bf16 v[152:155], v[120:123], v[168:171], v[152:155]
	v_mfma_f32_16x16x32_bf16 v[148:151], v[144:147], v[168:171], v[148:151]
	v_mfma_f32_16x16x32_bf16 v[128:131], v[120:123], v[176:179], v[128:131]
	v_mfma_f32_16x16x32_bf16 v[124:127], v[144:147], v[176:179], v[124:127]
	v_mfma_f32_16x16x32_bf16 v[104:107], v[120:123], v[184:187], v[104:107]
	v_mfma_f32_16x16x32_bf16 v[96:99], v[144:147], v[184:187], v[96:99]
	v_mfma_f32_16x16x32_bf16 v[76:79], v[120:123], v[208:211], v[76:79]
	v_mfma_f32_16x16x32_bf16 v[72:75], v[144:147], v[208:211], v[72:75]
	s_setprio 0
	s_barrier
	s_add_i32 s26, s54, s39
	v_lshl_add_u64 v[198:199], s[28:29], 0, v[192:193]
	s_mov_b32 m0, s26
	ds_read_b128 v[156:159], v236 offset:16384
	ds_read_b128 v[168:171], v236 offset:17408
	ds_read_b128 v[172:175], v236 offset:18432
	ds_read_b128 v[176:179], v236 offset:19456
	ds_read_b128 v[180:183], v236 offset:20480
	ds_read_b128 v[184:187], v236 offset:21504
	ds_read_b128 v[188:191], v236 offset:22528
	ds_read_b128 v[208:211], v236 offset:23552
	global_load_lds_dwordx4 v[198:199], off
	s_add_i32 m0, s26, 0x2000
	s_add_u32 s26, s28, 0xb0000
	v_lshl_add_u64 v[212:213], s[28:29], 0, v[202:203]
	s_addc_u32 s27, s29, 0
	s_add_i32 s54, s55, s39
	global_load_lds_dwordx4 v[212:213], off
	v_lshl_add_u64 v[214:215], s[26:27], 0, v[192:193]
	s_mov_b32 m0, s54
	v_lshl_add_u64 v[216:217], s[30:31], 0, v[194:195]
	global_load_lds_dwordx4 v[214:215], off
	s_add_i32 m0, s54, 0x2000
	v_lshl_add_u64 v[214:215], s[26:27], 0, v[202:203]
	global_load_lds_dwordx4 v[214:215], off
	s_mov_b32 m0, s40
	v_lshl_add_u64 v[214:215], s[30:31], 0, v[0:1]
	global_load_lds_dwordx4 v[214:215], off
	s_mov_b32 m0, s41
	s_nop 0
	global_load_lds_dwordx4 v[216:217], off
	s_waitcnt vmcnt(8)
	s_waitcnt lgkmcnt(0)
	s_barrier
; #define PG8_STAGE(bufoff, gbase, voff) do { _Pragma("unroll") for (int _i = 0; _i < 2; ++_i) \
;         __builtin_amdgcn_global_load_lds((const unsigned*)((const char*)(gbase) + (voff)[_i]), (PG8_LAS unsigned*)(lds + (bufoff) + ldsw + _i * 8192), 16, 0, 0); } while (0)
; #define PG8_LDA(dst, b, h) do { _Pragma("unroll") for (int m = 0; m < 4; ++m) _Pragma("unroll") for (int k = 0; k < 2; ++k) dst[m][k] = *(const PG8_LAS bf16x8*)(lds + PG8_SA(b, h) + aoff + m * 2048 + k * 1024); } while (0)
; #define PG8_LDB(dst, b, h) do { _Pragma("unroll") for (int n = 0; n < 2; ++n) _Pragma("unroll") for (int k = 0; k < 2; ++k) dst[n][k] = *(const PG8_LAS bf16x8*)(lds + PG8_SB(b, h) + boff + n * 2048 + k * 1024); } while (0)
; #define PG8_MMA(ai, bj, At, Bt) do { __builtin_amdgcn_s_setprio(1); _Pragma("unroll") for (int m = 0; m < 4; ++m) _Pragma("unroll") for (int n = 0; n < 2; ++n) _Pragma("unroll") for (int k = 0; k < 2; ++k) \
;         acc[ai][bj][m][n] = __builtin_amdgcn_mfma_f32_16x16x32_bf16(Bt[n][k], At[m][k], acc[ai][bj][m][n], 0, 0, 0); __builtin_amdgcn_s_setprio(0); } while (0)
; #define PG8_WAIT_V(n) asm volatile("s_waitcnt vmcnt(" #n ")" ::: "memory")
; #define PG8_WAIT_L(n) asm volatile("s_waitcnt lgkmcnt(" #n ")" ::: "memory")
; #define PG8_BAR __builtin_amdgcn_s_barrier()
; #define PG8_SCHED __builtin_amdgcn_sched_barrier(0)
; template <class Epi, class Sched, bool ALIGN_EPI = false, bool SP2 = false>
; __device__ __forceinline__ void gemm_phase(PG8_LAS unsigned char* lds, const Gemm g, const Sched& S, const Epi& E) {
;     ...
;             PG8_WAIT_V(8); PG8_WAIT_L(0); PG8_BAR; PG8_MMA(1, 0, At, B0); PG8_MMA(1, 1, At, B1); PG8_BAR; PG8_SCHED;
;             PG8_LDB(B0, 1, 0); PG8_LDB(B1, 1, 1); PG8_SCHED; PG8_LDA(At, 1, 0); PG8_STAGE(PG8_SA(0, 1), a2 + hstep, voffA);
;             PG8_WAIT_V(8); PG8_WAIT_L(0); PG8_BAR; PG8_MMA(0, 0, At, B0); PG8_MMA(0, 1, At, B1); PG8_BAR; PG8_SCHED;
	s_setprio 1
	s_waitcnt lgkmcnt(0)
	v_mfma_f32_16x16x32_bf16 v[64:67], v[68:71], v[156:159], v[64:67]
	v_mfma_f32_16x16x32_bf16 v[60:63], v[92:95], v[156:159], v[60:63]
	v_mfma_f32_16x16x32_bf16 v[48:51], v[68:71], v[172:175], v[48:51]
	v_mfma_f32_16x16x32_bf16 v[44:47], v[92:95], v[172:175], v[44:47]
	v_mfma_f32_16x16x32_bf16 v[32:35], v[68:71], v[180:183], v[32:35]
	v_mfma_f32_16x16x32_bf16 v[28:31], v[92:95], v[180:183], v[28:31]
	v_mfma_f32_16x16x32_bf16 v[16:19], v[68:71], v[188:191], v[16:19]
	v_mfma_f32_16x16x32_bf16 v[12:15], v[92:95], v[188:191], v[12:15]
	v_mfma_f32_16x16x32_bf16 v[64:67], v[80:83], v[168:171], v[64:67]
	v_mfma_f32_16x16x32_bf16 v[60:63], v[100:103], v[168:171], v[60:63]
	v_mfma_f32_16x16x32_bf16 v[48:51], v[80:83], v[176:179], v[48:51]
	v_mfma_f32_16x16x32_bf16 v[44:47], v[100:103], v[176:179], v[44:47]
	v_mfma_f32_16x16x32_bf16 v[32:35], v[80:83], v[184:187], v[32:35]
	v_mfma_f32_16x16x32_bf16 v[28:31], v[100:103], v[184:187], v[28:31]
	v_mfma_f32_16x16x32_bf16 v[16:19], v[80:83], v[208:211], v[16:19]
	v_mfma_f32_16x16x32_bf16 v[12:15], v[100:103], v[208:211], v[12:15]
	s_setprio 0
	s_setprio 1
	v_mfma_f32_16x16x32_bf16 v[56:59], v[112:115], v[156:159], v[56:59]
	v_mfma_f32_16x16x32_bf16 v[52:55], v[132:135], v[156:159], v[52:55]
	v_mfma_f32_16x16x32_bf16 v[40:43], v[112:115], v[172:175], v[40:43]
	v_mfma_f32_16x16x32_bf16 v[36:39], v[132:135], v[172:175], v[36:39]
	v_mfma_f32_16x16x32_bf16 v[24:27], v[112:115], v[180:183], v[24:27]
	v_mfma_f32_16x16x32_bf16 v[20:23], v[132:135], v[180:183], v[20:23]
	v_mfma_f32_16x16x32_bf16 v[8:11], v[112:115], v[188:191], v[8:11]
	v_mfma_f32_16x16x32_bf16 v[4:7], v[132:135], v[188:191], v[4:7]
	v_mfma_f32_16x16x32_bf16 v[56:59], v[120:123], v[168:171], v[56:59]
	v_mfma_f32_16x16x32_bf16 v[52:55], v[144:147], v[168:171], v[52:55]
	v_mfma_f32_16x16x32_bf16 v[40:43], v[120:123], v[176:179], v[40:43]
	v_mfma_f32_16x16x32_bf16 v[36:39], v[144:147], v[176:179], v[36:39]
	v_mfma_f32_16x16x32_bf16 v[24:27], v[120:123], v[184:187], v[24:27]
	v_mfma_f32_16x16x32_bf16 v[20:23], v[144:147], v[184:187], v[20:23]
	v_mfma_f32_16x16x32_bf16 v[8:11], v[120:123], v[208:211], v[8:11]
	v_mfma_f32_16x16x32_bf16 v[4:7], v[144:147], v[208:211], v[4:7]
	s_setprio 0
	s_barrier
	s_add_i32 s54, 0, 0x18000
	s_add_i32 s55, 0, 0x1c000
	v_add_u32_e32 v100, s54, v234
	v_add_u32_e32 v144, s55, v234
	ds_read_b128 v[68:71], v100
	ds_read_b128 v[80:83], v100 offset:1024
	ds_read_b128 v[92:95], v100 offset:2048
	ds_read_b128 v[100:103], v100 offset:3072
	ds_read_b128 v[112:115], v144
	ds_read_b128 v[120:123], v144 offset:1024
	ds_read_b128 v[132:135], v144 offset:2048
	ds_read_b128 v[144:147], v144 offset:3072
	s_add_u32 s26, s30, 0xb0000
	s_addc_u32 s27, s31, 0
	s_mov_b32 m0, s42
	v_lshl_add_u64 v[218:219], s[26:27], 0, v[0:1]
	ds_read_b128 v[156:159], v236 offset:32768
	ds_read_b128 v[168:171], v236 offset:33792
	ds_read_b128 v[172:175], v236 offset:34816
	ds_read_b128 v[176:179], v236 offset:35840
	ds_read_b128 v[180:183], v236 offset:36864
	ds_read_b128 v[184:187], v236 offset:37888
	ds_read_b128 v[188:191], v236 offset:38912
	ds_read_b128 v[208:211], v236 offset:39936
	global_load_lds_dwordx4 v[218:219], off
	s_mov_b32 m0, s43
	v_lshl_add_u64 v[218:219], s[26:27], 0, v[194:195]
	global_load_lds_dwordx4 v[218:219], off
	s_waitcnt vmcnt(8)
	s_waitcnt lgkmcnt(0)
	s_barrier
	s_setprio 1
	s_waitcnt lgkmcnt(0)
	v_mfma_f32_16x16x32_bf16 v[164:167], v[68:71], v[156:159], v[164:167]
	v_mfma_f32_16x16x32_bf16 v[160:163], v[92:95], v[156:159], v[160:163]
	v_mfma_f32_16x16x32_bf16 v[140:143], v[68:71], v[172:175], v[140:143]
	v_mfma_f32_16x16x32_bf16 v[136:139], v[92:95], v[172:175], v[136:139]
	v_mfma_f32_16x16x32_bf16 v[116:119], v[68:71], v[180:183], v[116:119]
	v_mfma_f32_16x16x32_bf16 v[108:111], v[92:95], v[180:183], v[108:111]
	v_mfma_f32_16x16x32_bf16 v[88:91], v[68:71], v[188:191], v[88:91]
	v_mfma_f32_16x16x32_bf16 v[84:87], v[92:95], v[188:191], v[84:87]
	v_mfma_f32_16x16x32_bf16 v[164:167], v[80:83], v[168:171], v[164:167]
	v_mfma_f32_16x16x32_bf16 v[160:163], v[100:103], v[168:171], v[160:163]
	v_mfma_f32_16x16x32_bf16 v[140:143], v[80:83], v[176:179], v[140:143]
	v_mfma_f32_16x16x32_bf16 v[136:139], v[100:103], v[176:179], v[136:139]
	v_mfma_f32_16x16x32_bf16 v[116:119], v[80:83], v[184:187], v[116:119]
	v_mfma_f32_16x16x32_bf16 v[108:111], v[100:103], v[184:187], v[108:111]
	v_mfma_f32_16x16x32_bf16 v[88:91], v[80:83], v[208:211], v[88:91]
	v_mfma_f32_16x16x32_bf16 v[84:87], v[100:103], v[208:211], v[84:87]
	s_setprio 0
	s_setprio 1
	v_mfma_f32_16x16x32_bf16 v[152:155], v[112:115], v[156:159], v[152:155]
	v_mfma_f32_16x16x32_bf16 v[148:151], v[132:135], v[156:159], v[148:151]
	v_mfma_f32_16x16x32_bf16 v[128:131], v[112:115], v[172:175], v[128:131]
	v_mfma_f32_16x16x32_bf16 v[124:127], v[132:135], v[172:175], v[124:127]
	v_mfma_f32_16x16x32_bf16 v[104:107], v[112:115], v[180:183], v[104:107]
	v_mfma_f32_16x16x32_bf16 v[96:99], v[132:135], v[180:183], v[96:99]
	v_mfma_f32_16x16x32_bf16 v[76:79], v[112:115], v[188:191], v[76:79]
	v_mfma_f32_16x16x32_bf16 v[72:75], v[132:135], v[188:191], v[72:75]
	v_mfma_f32_16x16x32_bf16 v[152:155], v[120:123], v[168:171], v[152:155]
	v_mfma_f32_16x16x32_bf16 v[148:151], v[144:147], v[168:171], v[148:151]
	v_mfma_f32_16x16x32_bf16 v[128:131], v[120:123], v[176:179], v[128:131]
	v_mfma_f32_16x16x32_bf16 v[124:127], v[144:147], v[176:179], v[124:127]
	v_mfma_f32_16x16x32_bf16 v[104:107], v[120:123], v[184:187], v[104:107]
	v_mfma_f32_16x16x32_bf16 v[96:99], v[144:147], v[184:187], v[96:99]
	v_mfma_f32_16x16x32_bf16 v[76:79], v[120:123], v[208:211], v[76:79]
	v_mfma_f32_16x16x32_bf16 v[72:75], v[144:147], v[208:211], v[72:75]
	s_setprio 0
	s_barrier
; #define PG8_STAGE(bufoff, gbase, voff) do { _Pragma("unroll") for (int _i = 0; _i < 2; ++_i) \
;         __builtin_amdgcn_global_load_lds((const unsigned*)((const char*)(gbase) + (voff)[_i]), (PG8_LAS unsigned*)(lds + (bufoff) + ldsw + _i * 8192), 16, 0, 0); } while (0)
; #define PG8_LDA(dst, b, h) do { _Pragma("unroll") for (int m = 0; m < 4; ++m) _Pragma("unroll") for (int k = 0; k < 2; ++k) dst[m][k] = *(const PG8_LAS bf16x8*)(lds + PG8_SA(b, h) + aoff + m * 2048 + k * 1024); } while (0)
; #define PG8_MMA(ai, bj, At, Bt) do { __builtin_amdgcn_s_setprio(1); _Pragma("unroll") for (int m = 0; m < 4; ++m) _Pragma("unroll") for (int n = 0; n < 2; ++n) _Pragma("unroll") for (int k = 0; k < 2; ++k) \
;         acc[ai][bj][m][n] = __builtin_amdgcn_mfma_f32_16x16x32_bf16(Bt[n][k], At[m][k], acc[ai][bj][m][n], 0, 0, 0); __builtin_amdgcn_s_setprio(0); } while (0)
; #define PG8_WAIT_V(n) asm volatile("s_waitcnt vmcnt(" #n ")" ::: "memory")
; #define PG8_WAIT_L(n) asm volatile("s_waitcnt lgkmcnt(" #n ")" ::: "memory")
; #define PG8_BAR __builtin_amdgcn_s_barrier()
; #define PG8_SCHED __builtin_amdgcn_sched_barrier(0)
; template <class Epi, class Sched, bool ALIGN_EPI = false, bool SP2 = false>
; __device__ __forceinline__ void gemm_phase(PG8_LAS unsigned char* lds, const Gemm g, const Sched& S, const Epi& E) {
;     ...
;             PG8_LDA(At, 1, 1); PG8_STAGE(PG8_SB(1, 0), b3, voffB); PG8_STAGE(PG8_SB(1, 1), b3 + hstep, voffB); PG8_STAGE(PG8_SA(1, 0), a3, voffA);
;             PG8_WAIT_V(8); PG8_WAIT_L(0); PG8_BAR; PG8_MMA(1, 0, At, B0); PG8_MMA(1, 1, At, B1); PG8_BAR; PG8_SCHED;
;     ...
;         if constexpr (ALIGN_EPI) { if (wr == 0) PG8_BAR; }
	s_add_i32 s26, s54, s39
	v_lshl_add_u64 v[198:199], v[198:199], 0, s[82:83]
	s_mov_b32 m0, s26
	ds_read_b128 v[156:159], v236 offset:49152
	ds_read_b128 v[168:171], v236 offset:50176
	ds_read_b128 v[172:175], v236 offset:51200
	ds_read_b128 v[176:179], v236 offset:52224
	ds_read_b128 v[180:183], v236 offset:53248
	ds_read_b128 v[184:187], v236 offset:54272
	ds_read_b128 v[188:191], v236 offset:55296
	ds_read_b128 v[208:211], v236 offset:56320
	global_load_lds_dwordx4 v[198:199], off
	s_add_i32 m0, s26, 0x2000
	s_add_u32 s26, s28, 0xb0080
	v_lshl_add_u64 v[198:199], v[212:213], 0, s[82:83]
	s_addc_u32 s27, s29, 0
	s_add_i32 s28, s55, s39
	global_load_lds_dwordx4 v[198:199], off
	s_mov_b32 m0, s28
	v_lshl_add_u64 v[198:199], s[26:27], 0, v[192:193]
	global_load_lds_dwordx4 v[198:199], off
	s_add_i32 m0, s28, 0x2000
	v_lshl_add_u64 v[198:199], s[26:27], 0, v[202:203]
	global_load_lds_dwordx4 v[198:199], off
	s_mov_b32 m0, s47
	v_lshl_add_u64 v[198:199], v[214:215], 0, s[82:83]
	global_load_lds_dwordx4 v[198:199], off
	s_mov_b32 m0, s48
	v_lshl_add_u64 v[198:199], v[216:217], 0, s[82:83]
	global_load_lds_dwordx4 v[198:199], off
	s_waitcnt vmcnt(8)
	s_waitcnt lgkmcnt(0)
	s_barrier
	s_setprio 1
	s_waitcnt lgkmcnt(0)
	v_mfma_f32_16x16x32_bf16 v[64:67], v[68:71], v[156:159], v[64:67]
	v_mfma_f32_16x16x32_bf16 v[60:63], v[92:95], v[156:159], v[60:63]
	v_mfma_f32_16x16x32_bf16 v[48:51], v[68:71], v[172:175], v[48:51]
	v_mfma_f32_16x16x32_bf16 v[44:47], v[92:95], v[172:175], v[44:47]
	v_mfma_f32_16x16x32_bf16 v[32:35], v[68:71], v[180:183], v[32:35]
	v_mfma_f32_16x16x32_bf16 v[28:31], v[92:95], v[180:183], v[28:31]
	v_mfma_f32_16x16x32_bf16 v[16:19], v[68:71], v[188:191], v[16:19]
	v_mfma_f32_16x16x32_bf16 v[12:15], v[92:95], v[188:191], v[12:15]
	v_mfma_f32_16x16x32_bf16 v[64:67], v[80:83], v[168:171], v[64:67]
	v_mfma_f32_16x16x32_bf16 v[60:63], v[100:103], v[168:171], v[60:63]
	v_mfma_f32_16x16x32_bf16 v[48:51], v[80:83], v[176:179], v[48:51]
	v_mfma_f32_16x16x32_bf16 v[44:47], v[100:103], v[176:179], v[44:47]
	v_mfma_f32_16x16x32_bf16 v[32:35], v[80:83], v[184:187], v[32:35]
	v_mfma_f32_16x16x32_bf16 v[28:31], v[100:103], v[184:187], v[28:31]
	v_mfma_f32_16x16x32_bf16 v[16:19], v[80:83], v[208:211], v[16:19]
	v_mfma_f32_16x16x32_bf16 v[12:15], v[100:103], v[208:211], v[12:15]
	s_setprio 0
	s_setprio 1
	v_mfma_f32_16x16x32_bf16 v[56:59], v[112:115], v[156:159], v[56:59]
	v_mfma_f32_16x16x32_bf16 v[52:55], v[132:135], v[156:159], v[52:55]
	v_mfma_f32_16x16x32_bf16 v[40:43], v[112:115], v[172:175], v[40:43]
	v_mfma_f32_16x16x32_bf16 v[36:39], v[132:135], v[172:175], v[36:39]
	v_mfma_f32_16x16x32_bf16 v[24:27], v[112:115], v[180:183], v[24:27]
	v_mfma_f32_16x16x32_bf16 v[20:23], v[132:135], v[180:183], v[20:23]
	v_mfma_f32_16x16x32_bf16 v[8:11], v[112:115], v[188:191], v[8:11]
	v_mfma_f32_16x16x32_bf16 v[4:7], v[132:135], v[188:191], v[4:7]
	v_mfma_f32_16x16x32_bf16 v[56:59], v[120:123], v[168:171], v[56:59]
	v_mfma_f32_16x16x32_bf16 v[52:55], v[144:147], v[168:171], v[52:55]
	v_mfma_f32_16x16x32_bf16 v[40:43], v[120:123], v[176:179], v[40:43]
	v_mfma_f32_16x16x32_bf16 v[36:39], v[144:147], v[176:179], v[36:39]
	v_mfma_f32_16x16x32_bf16 v[24:27], v[120:123], v[184:187], v[24:27]
	v_mfma_f32_16x16x32_bf16 v[20:23], v[144:147], v[184:187], v[20:23]
	v_mfma_f32_16x16x32_bf16 v[8:11], v[120:123], v[208:211], v[8:11]
	v_mfma_f32_16x16x32_bf16 v[4:7], v[144:147], v[208:211], v[4:7]
	s_setprio 0
	s_barrier
	s_add_i32 s53, s53, 2
	s_add_u32 s44, s44, 0x100
	s_addc_u32 s45, s45, 0
	s_cmp_gt_u32 s53, 41
	s_mov_b64 s[26:27], s[8:9]
	s_cbranch_scc0 .LBB0_480
	s_and_b64 vcc, exec, s[20:21]
	s_cbranch_vccz .LBB0_483
	s_barrier
